# GEMM loops: loop-counter/exit-test SALU moved above the loop-back barrier (back-edge rotation, asm guide 7.11)
# baseline (speedup 1.0000x reference)
; #define PG8_STAGE(bufoff, gbase, voff) do { _Pragma("unroll") for (int _i = 0; _i < 2; ++_i) \
;         __builtin_amdgcn_global_load_lds((const unsigned*)((const char*)(gbase) + (voff)[_i]), (PG8_LAS unsigned*)(lds + (bufoff) + ldsw + _i * 8192), 16, 0, 0); } while (0)
; #define PG8_LDA(dst, b, h) do { _Pragma("unroll") for (int m = 0; m < 4; ++m) _Pragma("unroll") for (int k = 0; k < 2; ++k) dst[m][k] = *(const PG8_LAS bf16x8*)(lds + PG8_SA(b, h) + aoff + m * 2048 + k * 1024); } while (0)
; #define PG8_LDB(dst, b, h) do { _Pragma("unroll") for (int n = 0; n < 2; ++n) _Pragma("unroll") for (int k = 0; k < 2; ++k) dst[n][k] = *(const PG8_LAS bf16x8*)(lds + PG8_SB(b, h) + boff + n * 2048 + k * 1024); } while (0)
; #define PG8_MMA(ai, bj, At, Bt) do { __builtin_amdgcn_s_setprio(1); _Pragma("unroll") for (int m = 0; m < 4; ++m) _Pragma("unroll") for (int n = 0; n < 2; ++n) _Pragma("unroll") for (int k = 0; k < 2; ++k) \
;         acc[ai][bj][m][n] = __builtin_amdgcn_mfma_f32_16x16x32_bf16(Bt[n][k], At[m][k], acc[ai][bj][m][n], 0, 0, 0); __builtin_amdgcn_s_setprio(0); } while (0)
; #define PG8_WAIT_V(n) asm volatile("s_waitcnt vmcnt(" #n ")" ::: "memory")
; #define PG8_WAIT_L(n) asm volatile("s_waitcnt lgkmcnt(" #n ")" ::: "memory")
; #define PG8_BAR __builtin_amdgcn_s_barrier()
; #define PG8_SCHED __builtin_amdgcn_sched_barrier(0)
; template <class Epi, bool BLKDIAG = false>
; __device__ __forceinline__ void gemm_phase(PG8_LAS unsigned char* lds, const Gemm g, const StaticOrder& S, const Epi& E) {
;     ...
;             const char* a1 = cA + (size_t)(t + 1) * kstep;
;             const char* a2 = last ? nA : cA + (size_t)(t + 2) * kstep; const char* b2 = last ? nB : cB + (size_t)(t + 2) * kstep;
;             const char* a3 = a2 + kstep; const char* b3 = b2 + kstep;
;             PG8_LDB(B0, 0, 0); PG8_LDB(B1, 0, 1); PG8_SCHED; PG8_LDA(At, 0, 0); PG8_STAGE(PG8_SA(1, 1), a1 + hstepA, voffA);
;             PG8_WAIT_V(8); PG8_WAIT_L(0); PG8_BAR; if (lo_) PG8_MMA(0, 0, At, B0); if (hi_) PG8_MMA(0, 1, At, B1); PG8_BAR; PG8_SCHED;
;             PG8_LDA(At, 0, 1); PG8_STAGE(PG8_SB(0, 0), b2, voffB); PG8_STAGE(PG8_SB(0, 1), b2 + hstepB, voffB); PG8_STAGE(PG8_SA(0, 0), a2, voffA);
;             PG8_WAIT_V(8); PG8_WAIT_L(0); PG8_BAR; if (lo_) PG8_MMA(1, 0, At, B0); if (hi_) PG8_MMA(1, 1, At, B1); PG8_BAR; PG8_SCHED;
.LBB0_136:
	ds_read_b128 v[156:159], v172
	ds_read_b128 v[160:163], v172 offset:1024
	ds_read_b128 v[164:167], v172 offset:2048
	ds_read_b128 v[176:179], v172 offset:3072
	ds_read_b128 v[180:183], v173
	ds_read_b128 v[184:187], v173 offset:1024
	ds_read_b128 v[190:193], v173 offset:2048
	ds_read_b128 v[194:197], v173 offset:3072
	s_add_u32 s12, s10, 0xfff80080
	s_addc_u32 s13, s11, -1
	s_cmp_eq_u32 s65, 28
	s_cselect_b32 s15, s7, s13
	s_cselect_b32 s14, s9, s12
	s_cselect_b32 s13, s44, s61
	s_cselect_b32 s12, s45, s60
	v_lshl_add_u64 v[168:169], s[10:11], 0, v[148:149]
	s_add_i32 m0, s74, 0xc000
	ds_read_b128 v[198:201], v174
	ds_read_b128 v[202:205], v174 offset:1024
	ds_read_b128 v[208:211], v174 offset:2048
	ds_read_b128 v[212:215], v174 offset:3072
	ds_read_b128 v[216:219], v174 offset:4096
	ds_read_b128 v[220:223], v174 offset:5120
	ds_read_b128 v[224:227], v174 offset:6144
	ds_read_b128 v[228:231], v174 offset:7168
	global_load_lds_dwordx4 v[168:169], off
	v_lshl_add_u64 v[168:169], s[10:11], 0, v[150:151]
	s_add_i32 m0, s74, 0xe000
	s_nop 0
	global_load_lds_dwordx4 v[168:169], off
	s_waitcnt vmcnt(8)
	s_waitcnt lgkmcnt(0)
	s_barrier
	s_setprio 1
	s_waitcnt lgkmcnt(0)
	v_mfma_f32_16x16x32_bf16 v[124:127], v[156:159], v[198:201], v[124:127]
	v_mfma_f32_16x16x32_bf16 v[120:123], v[164:167], v[198:201], v[120:123]
	v_mfma_f32_16x16x32_bf16 v[108:111], v[156:159], v[208:211], v[108:111]
	v_mfma_f32_16x16x32_bf16 v[104:107], v[164:167], v[208:211], v[104:107]
	v_mfma_f32_16x16x32_bf16 v[92:95], v[156:159], v[216:219], v[92:95]
	v_mfma_f32_16x16x32_bf16 v[88:91], v[164:167], v[216:219], v[88:91]
	v_mfma_f32_16x16x32_bf16 v[76:79], v[156:159], v[224:227], v[76:79]
	v_mfma_f32_16x16x32_bf16 v[72:75], v[164:167], v[224:227], v[72:75]
	v_mfma_f32_16x16x32_bf16 v[124:127], v[160:163], v[202:205], v[124:127]
	v_mfma_f32_16x16x32_bf16 v[120:123], v[176:179], v[202:205], v[120:123]
	v_mfma_f32_16x16x32_bf16 v[108:111], v[160:163], v[212:215], v[108:111]
	v_mfma_f32_16x16x32_bf16 v[104:107], v[176:179], v[212:215], v[104:107]
	v_mfma_f32_16x16x32_bf16 v[92:95], v[160:163], v[220:223], v[92:95]
	v_mfma_f32_16x16x32_bf16 v[88:91], v[176:179], v[220:223], v[88:91]
	v_mfma_f32_16x16x32_bf16 v[76:79], v[160:163], v[228:231], v[76:79]
	v_mfma_f32_16x16x32_bf16 v[72:75], v[176:179], v[228:231], v[72:75]
	s_setprio 0
	s_setprio 1
	v_mfma_f32_16x16x32_bf16 v[116:119], v[180:183], v[198:201], v[116:119]
	v_mfma_f32_16x16x32_bf16 v[112:115], v[190:193], v[198:201], v[112:115]
	v_mfma_f32_16x16x32_bf16 v[100:103], v[180:183], v[208:211], v[100:103]
	v_mfma_f32_16x16x32_bf16 v[96:99], v[190:193], v[208:211], v[96:99]
	v_mfma_f32_16x16x32_bf16 v[84:87], v[180:183], v[216:219], v[84:87]
	v_mfma_f32_16x16x32_bf16 v[80:83], v[190:193], v[216:219], v[80:83]
	v_mfma_f32_16x16x32_bf16 v[68:71], v[180:183], v[224:227], v[68:71]
	v_mfma_f32_16x16x32_bf16 v[64:67], v[190:193], v[224:227], v[64:67]
	v_mfma_f32_16x16x32_bf16 v[116:119], v[184:187], v[202:205], v[116:119]
	v_mfma_f32_16x16x32_bf16 v[112:115], v[194:197], v[202:205], v[112:115]
	v_mfma_f32_16x16x32_bf16 v[100:103], v[184:187], v[212:215], v[100:103]
	v_mfma_f32_16x16x32_bf16 v[96:99], v[194:197], v[212:215], v[96:99]
	v_mfma_f32_16x16x32_bf16 v[84:87], v[184:187], v[220:223], v[84:87]
	v_mfma_f32_16x16x32_bf16 v[80:83], v[194:197], v[220:223], v[80:83]
	v_mfma_f32_16x16x32_bf16 v[68:71], v[184:187], v[228:231], v[68:71]
	v_mfma_f32_16x16x32_bf16 v[64:67], v[194:197], v[228:231], v[64:67]
	s_setprio 0
	s_barrier
	s_add_i32 s70, s63, s35
	v_lshl_add_u64 v[168:169], s[12:13], 0, v[130:131]
	s_mov_b32 m0, s70
	ds_read_b128 v[198:201], v174 offset:16384
	ds_read_b128 v[202:205], v174 offset:17408
	ds_read_b128 v[208:211], v174 offset:18432
	ds_read_b128 v[212:215], v174 offset:19456
	ds_read_b128 v[216:219], v174 offset:20480
	ds_read_b128 v[220:223], v174 offset:21504
	ds_read_b128 v[224:227], v174 offset:22528
	ds_read_b128 v[228:231], v174 offset:23552
	global_load_lds_dwordx4 v[168:169], off
	s_add_i32 m0, s70, 0x2000
	s_add_u32 s70, s12, 0x80000
	v_lshl_add_u64 v[232:233], s[12:13], 0, v[134:135]
	s_addc_u32 s71, s13, 0
	s_add_i32 s78, s64, s35
	global_load_lds_dwordx4 v[232:233], off
	v_lshl_add_u64 v[234:235], s[70:71], 0, v[130:131]
	s_mov_b32 m0, s78
	v_lshl_add_u64 v[236:237], s[14:15], 0, v[132:133]
	global_load_lds_dwordx4 v[234:235], off
	v_lshl_add_u64 v[234:235], s[70:71], 0, v[134:135]
	s_add_i32 m0, s78, 0x2000
	s_nop 0
	global_load_lds_dwordx4 v[234:235], off
	v_lshl_add_u64 v[234:235], s[14:15], 0, v[128:129]
	s_mov_b32 m0, s74
	s_nop 0
	global_load_lds_dwordx4 v[234:235], off
	s_mov_b32 m0, s75
	s_nop 0
	global_load_lds_dwordx4 v[236:237], off
	s_waitcnt vmcnt(8)
	s_waitcnt lgkmcnt(0)
	s_barrier
; #define PG8_STAGE(bufoff, gbase, voff) do { _Pragma("unroll") for (int _i = 0; _i < 2; ++_i) \
;         __builtin_amdgcn_global_load_lds((const unsigned*)((const char*)(gbase) + (voff)[_i]), (PG8_LAS unsigned*)(lds + (bufoff) + ldsw + _i * 8192), 16, 0, 0); } while (0)
; #define PG8_LDA(dst, b, h) do { _Pragma("unroll") for (int m = 0; m < 4; ++m) _Pragma("unroll") for (int k = 0; k < 2; ++k) dst[m][k] = *(const PG8_LAS bf16x8*)(lds + PG8_SA(b, h) + aoff + m * 2048 + k * 1024); } while (0)
; #define PG8_LDB(dst, b, h) do { _Pragma("unroll") for (int n = 0; n < 2; ++n) _Pragma("unroll") for (int k = 0; k < 2; ++k) dst[n][k] = *(const PG8_LAS bf16x8*)(lds + PG8_SB(b, h) + boff + n * 2048 + k * 1024); } while (0)
; #define PG8_MMA(ai, bj, At, Bt) do { __builtin_amdgcn_s_setprio(1); _Pragma("unroll") for (int m = 0; m < 4; ++m) _Pragma("unroll") for (int n = 0; n < 2; ++n) _Pragma("unroll") for (int k = 0; k < 2; ++k) \
;         acc[ai][bj][m][n] = __builtin_amdgcn_mfma_f32_16x16x32_bf16(Bt[n][k], At[m][k], acc[ai][bj][m][n], 0, 0, 0); __builtin_amdgcn_s_setprio(0); } while (0)
; #define PG8_WAIT_V(n) asm volatile("s_waitcnt vmcnt(" #n ")" ::: "memory")
; #define PG8_WAIT_L(n) asm volatile("s_waitcnt lgkmcnt(" #n ")" ::: "memory")
; #define PG8_BAR __builtin_amdgcn_s_barrier()
; #define PG8_SCHED __builtin_amdgcn_sched_barrier(0)
; template <class Epi, bool BLKDIAG = false>
; __device__ __forceinline__ void gemm_phase(PG8_LAS unsigned char* lds, const Gemm g, const StaticOrder& S, const Epi& E) {
;     ...
;             PG8_WAIT_V(8); PG8_WAIT_L(0); PG8_BAR; if (lo_) PG8_MMA(1, 0, At, B0); if (hi_) PG8_MMA(1, 1, At, B1); PG8_BAR; PG8_SCHED;
;             PG8_LDB(B0, 1, 0); PG8_LDB(B1, 1, 1); PG8_SCHED; PG8_LDA(At, 1, 0); PG8_STAGE(PG8_SA(0, 1), a2 + hstepA, voffA);
;             PG8_WAIT_V(8); PG8_WAIT_L(0); PG8_BAR; if (lo_) PG8_MMA(0, 0, At, B0); if (hi_) PG8_MMA(0, 1, At, B1); PG8_BAR; PG8_SCHED;
	s_setprio 1
	s_waitcnt lgkmcnt(0)
	v_mfma_f32_16x16x32_bf16 v[60:63], v[156:159], v[198:201], v[60:63]
	v_mfma_f32_16x16x32_bf16 v[56:59], v[164:167], v[198:201], v[56:59]
	v_mfma_f32_16x16x32_bf16 v[44:47], v[156:159], v[208:211], v[44:47]
	v_mfma_f32_16x16x32_bf16 v[40:43], v[164:167], v[208:211], v[40:43]
	v_mfma_f32_16x16x32_bf16 v[28:31], v[156:159], v[216:219], v[28:31]
	v_mfma_f32_16x16x32_bf16 v[24:27], v[164:167], v[216:219], v[24:27]
	v_mfma_f32_16x16x32_bf16 v[12:15], v[156:159], v[224:227], v[12:15]
	v_mfma_f32_16x16x32_bf16 v[8:11], v[164:167], v[224:227], v[8:11]
	v_mfma_f32_16x16x32_bf16 v[60:63], v[160:163], v[202:205], v[60:63]
	v_mfma_f32_16x16x32_bf16 v[56:59], v[176:179], v[202:205], v[56:59]
	v_mfma_f32_16x16x32_bf16 v[44:47], v[160:163], v[212:215], v[44:47]
	v_mfma_f32_16x16x32_bf16 v[40:43], v[176:179], v[212:215], v[40:43]
	v_mfma_f32_16x16x32_bf16 v[28:31], v[160:163], v[220:223], v[28:31]
	v_mfma_f32_16x16x32_bf16 v[24:27], v[176:179], v[220:223], v[24:27]
	v_mfma_f32_16x16x32_bf16 v[12:15], v[160:163], v[228:231], v[12:15]
	v_mfma_f32_16x16x32_bf16 v[8:11], v[176:179], v[228:231], v[8:11]
	s_setprio 0
	s_setprio 1
	v_mfma_f32_16x16x32_bf16 v[52:55], v[180:183], v[198:201], v[52:55]
	v_mfma_f32_16x16x32_bf16 v[48:51], v[190:193], v[198:201], v[48:51]
	v_mfma_f32_16x16x32_bf16 v[36:39], v[180:183], v[208:211], v[36:39]
	v_mfma_f32_16x16x32_bf16 v[32:35], v[190:193], v[208:211], v[32:35]
	v_mfma_f32_16x16x32_bf16 v[20:23], v[180:183], v[216:219], v[20:23]
	v_mfma_f32_16x16x32_bf16 v[16:19], v[190:193], v[216:219], v[16:19]
	v_mfma_f32_16x16x32_bf16 v[4:7], v[180:183], v[224:227], v[4:7]
	v_mfma_f32_16x16x32_bf16 v[0:3], v[190:193], v[224:227], v[0:3]
	v_mfma_f32_16x16x32_bf16 v[52:55], v[184:187], v[202:205], v[52:55]
	v_mfma_f32_16x16x32_bf16 v[48:51], v[194:197], v[202:205], v[48:51]
	v_mfma_f32_16x16x32_bf16 v[36:39], v[184:187], v[212:215], v[36:39]
	v_mfma_f32_16x16x32_bf16 v[32:35], v[194:197], v[212:215], v[32:35]
	v_mfma_f32_16x16x32_bf16 v[20:23], v[184:187], v[220:223], v[20:23]
	v_mfma_f32_16x16x32_bf16 v[16:19], v[194:197], v[220:223], v[16:19]
	v_mfma_f32_16x16x32_bf16 v[4:7], v[184:187], v[228:231], v[4:7]
	v_mfma_f32_16x16x32_bf16 v[0:3], v[194:197], v[228:231], v[0:3]
	s_setprio 0
	s_barrier
	s_add_i32 s70, 0, 0x18000
	v_add_u32_e32 v136, s70, v171
	s_add_i32 s71, 0, 0x1c000
	ds_read_b128 v[156:159], v136
	ds_read_b128 v[160:163], v136 offset:1024
	ds_read_b128 v[164:167], v136 offset:2048
	ds_read_b128 v[176:179], v136 offset:3072
	v_add_u32_e32 v136, s71, v171
	ds_read_b128 v[180:183], v136
	ds_read_b128 v[184:187], v136 offset:1024
	ds_read_b128 v[190:193], v136 offset:2048
	ds_read_b128 v[194:197], v136 offset:3072
	s_add_u32 s14, s14, 0x80000
	s_addc_u32 s15, s15, 0
	s_mov_b32 m0, s18
	v_lshl_add_u64 v[238:239], s[14:15], 0, v[128:129]
	ds_read_b128 v[198:201], v174 offset:32768
	ds_read_b128 v[202:205], v174 offset:33792
	ds_read_b128 v[208:211], v174 offset:34816
	ds_read_b128 v[212:215], v174 offset:35840
	ds_read_b128 v[216:219], v174 offset:36864
	ds_read_b128 v[220:223], v174 offset:37888
	ds_read_b128 v[224:227], v174 offset:38912
	ds_read_b128 v[228:231], v174 offset:39936
	global_load_lds_dwordx4 v[238:239], off
	v_lshl_add_u64 v[238:239], s[14:15], 0, v[132:133]
	s_mov_b32 m0, s19
	s_nop 0
	global_load_lds_dwordx4 v[238:239], off
	s_waitcnt vmcnt(8)
	s_waitcnt lgkmcnt(0)
	s_barrier
	s_setprio 1
	s_waitcnt lgkmcnt(0)
	v_mfma_f32_16x16x32_bf16 v[124:127], v[156:159], v[198:201], v[124:127]
	v_mfma_f32_16x16x32_bf16 v[120:123], v[164:167], v[198:201], v[120:123]
	v_mfma_f32_16x16x32_bf16 v[108:111], v[156:159], v[208:211], v[108:111]
	v_mfma_f32_16x16x32_bf16 v[104:107], v[164:167], v[208:211], v[104:107]
	v_mfma_f32_16x16x32_bf16 v[92:95], v[156:159], v[216:219], v[92:95]
	v_mfma_f32_16x16x32_bf16 v[88:91], v[164:167], v[216:219], v[88:91]
	v_mfma_f32_16x16x32_bf16 v[76:79], v[156:159], v[224:227], v[76:79]
	v_mfma_f32_16x16x32_bf16 v[72:75], v[164:167], v[224:227], v[72:75]
	v_mfma_f32_16x16x32_bf16 v[124:127], v[160:163], v[202:205], v[124:127]
	v_mfma_f32_16x16x32_bf16 v[120:123], v[176:179], v[202:205], v[120:123]
	v_mfma_f32_16x16x32_bf16 v[108:111], v[160:163], v[212:215], v[108:111]
	v_mfma_f32_16x16x32_bf16 v[104:107], v[176:179], v[212:215], v[104:107]
	v_mfma_f32_16x16x32_bf16 v[92:95], v[160:163], v[220:223], v[92:95]
	v_mfma_f32_16x16x32_bf16 v[88:91], v[176:179], v[220:223], v[88:91]
	v_mfma_f32_16x16x32_bf16 v[76:79], v[160:163], v[228:231], v[76:79]
	v_mfma_f32_16x16x32_bf16 v[72:75], v[176:179], v[228:231], v[72:75]
	s_setprio 0
	s_setprio 1
	v_mfma_f32_16x16x32_bf16 v[116:119], v[180:183], v[198:201], v[116:119]
	v_mfma_f32_16x16x32_bf16 v[112:115], v[190:193], v[198:201], v[112:115]
	v_mfma_f32_16x16x32_bf16 v[100:103], v[180:183], v[208:211], v[100:103]
	v_mfma_f32_16x16x32_bf16 v[96:99], v[190:193], v[208:211], v[96:99]
	v_mfma_f32_16x16x32_bf16 v[84:87], v[180:183], v[216:219], v[84:87]
	v_mfma_f32_16x16x32_bf16 v[80:83], v[190:193], v[216:219], v[80:83]
	v_mfma_f32_16x16x32_bf16 v[68:71], v[180:183], v[224:227], v[68:71]
	v_mfma_f32_16x16x32_bf16 v[64:67], v[190:193], v[224:227], v[64:67]
	v_mfma_f32_16x16x32_bf16 v[116:119], v[184:187], v[202:205], v[116:119]
	v_mfma_f32_16x16x32_bf16 v[112:115], v[194:197], v[202:205], v[112:115]
	v_mfma_f32_16x16x32_bf16 v[100:103], v[184:187], v[212:215], v[100:103]
	v_mfma_f32_16x16x32_bf16 v[96:99], v[194:197], v[212:215], v[96:99]
	v_mfma_f32_16x16x32_bf16 v[84:87], v[184:187], v[220:223], v[84:87]
	v_mfma_f32_16x16x32_bf16 v[80:83], v[194:197], v[220:223], v[80:83]
	v_mfma_f32_16x16x32_bf16 v[68:71], v[184:187], v[228:231], v[68:71]
	v_mfma_f32_16x16x32_bf16 v[64:67], v[194:197], v[228:231], v[64:67]
	s_setprio 0
	s_barrier
; #define PG8_STAGE(bufoff, gbase, voff) do { _Pragma("unroll") for (int _i = 0; _i < 2; ++_i) \
;         __builtin_amdgcn_global_load_lds((const unsigned*)((const char*)(gbase) + (voff)[_i]), (PG8_LAS unsigned*)(lds + (bufoff) + ldsw + _i * 8192), 16, 0, 0); } while (0)
; #define PG8_LDA(dst, b, h) do { _Pragma("unroll") for (int m = 0; m < 4; ++m) _Pragma("unroll") for (int k = 0; k < 2; ++k) dst[m][k] = *(const PG8_LAS bf16x8*)(lds + PG8_SA(b, h) + aoff + m * 2048 + k * 1024); } while (0)
; #define PG8_MMA(ai, bj, At, Bt) do { __builtin_amdgcn_s_setprio(1); _Pragma("unroll") for (int m = 0; m < 4; ++m) _Pragma("unroll") for (int n = 0; n < 2; ++n) _Pragma("unroll") for (int k = 0; k < 2; ++k) \
;         acc[ai][bj][m][n] = __builtin_amdgcn_mfma_f32_16x16x32_bf16(Bt[n][k], At[m][k], acc[ai][bj][m][n], 0, 0, 0); __builtin_amdgcn_s_setprio(0); } while (0)
; #define PG8_WAIT_V(n) asm volatile("s_waitcnt vmcnt(" #n ")" ::: "memory")
; #define PG8_WAIT_L(n) asm volatile("s_waitcnt lgkmcnt(" #n ")" ::: "memory")
; #define PG8_BAR __builtin_amdgcn_s_barrier()
; #define PG8_SCHED __builtin_amdgcn_sched_barrier(0)
; template <class Epi, bool BLKDIAG = false>
; __device__ __forceinline__ void gemm_phase(PG8_LAS unsigned char* lds, const Gemm g, const StaticOrder& S, const Epi& E) {
;     ...
;             PG8_LDA(At, 1, 1); PG8_STAGE(PG8_SB(1, 0), b3, voffB); PG8_STAGE(PG8_SB(1, 1), b3 + hstepB, voffB); PG8_STAGE(PG8_SA(1, 0), a3, voffA);
;             PG8_WAIT_V(8); PG8_WAIT_L(0); PG8_BAR; if (lo_) PG8_MMA(1, 0, At, B0); if (hi_) PG8_MMA(1, 1, At, B1); PG8_BAR; PG8_SCHED;
;         }
;         if (wr == 0) PG8_BAR;
	s_add_i32 s14, s70, s35
	v_lshl_add_u64 v[168:169], v[168:169], 0, s[82:83]
	s_mov_b32 m0, s14
	ds_read_b128 v[198:201], v174 offset:49152
	ds_read_b128 v[202:205], v174 offset:50176
	ds_read_b128 v[208:211], v174 offset:51200
	ds_read_b128 v[212:215], v174 offset:52224
	ds_read_b128 v[216:219], v174 offset:53248
	ds_read_b128 v[220:223], v174 offset:54272
	ds_read_b128 v[224:227], v174 offset:55296
	ds_read_b128 v[228:231], v174 offset:56320
	global_load_lds_dwordx4 v[168:169], off
	s_add_i32 m0, s14, 0x2000
	s_add_u32 s12, s12, 0x80080
	v_lshl_add_u64 v[168:169], v[232:233], 0, s[82:83]
	s_addc_u32 s13, s13, 0
	s_add_i32 s14, s71, s35
	global_load_lds_dwordx4 v[168:169], off
	v_lshl_add_u64 v[168:169], s[12:13], 0, v[130:131]
	s_mov_b32 m0, s14
	s_nop 0
	global_load_lds_dwordx4 v[168:169], off
	v_lshl_add_u64 v[168:169], s[12:13], 0, v[134:135]
	s_add_i32 m0, s14, 0x2000
	s_nop 0
	global_load_lds_dwordx4 v[168:169], off
	v_lshl_add_u64 v[168:169], v[234:235], 0, s[82:83]
	s_mov_b32 m0, s81
	s_nop 0
	global_load_lds_dwordx4 v[168:169], off
	v_lshl_add_u64 v[168:169], v[236:237], 0, s[82:83]
	s_mov_b32 m0, s62
	s_nop 0
	global_load_lds_dwordx4 v[168:169], off
	s_waitcnt vmcnt(8)
	s_waitcnt lgkmcnt(0)
	s_barrier
	s_setprio 1
	s_waitcnt lgkmcnt(0)
	v_mfma_f32_16x16x32_bf16 v[60:63], v[156:159], v[198:201], v[60:63]
	v_mfma_f32_16x16x32_bf16 v[56:59], v[164:167], v[198:201], v[56:59]
	v_mfma_f32_16x16x32_bf16 v[44:47], v[156:159], v[208:211], v[44:47]
	v_mfma_f32_16x16x32_bf16 v[40:43], v[164:167], v[208:211], v[40:43]
	v_mfma_f32_16x16x32_bf16 v[28:31], v[156:159], v[216:219], v[28:31]
	v_mfma_f32_16x16x32_bf16 v[24:27], v[164:167], v[216:219], v[24:27]
	v_mfma_f32_16x16x32_bf16 v[12:15], v[156:159], v[224:227], v[12:15]
	v_mfma_f32_16x16x32_bf16 v[8:11], v[164:167], v[224:227], v[8:11]
	v_mfma_f32_16x16x32_bf16 v[60:63], v[160:163], v[202:205], v[60:63]
	v_mfma_f32_16x16x32_bf16 v[56:59], v[176:179], v[202:205], v[56:59]
	v_mfma_f32_16x16x32_bf16 v[44:47], v[160:163], v[212:215], v[44:47]
	v_mfma_f32_16x16x32_bf16 v[40:43], v[176:179], v[212:215], v[40:43]
	v_mfma_f32_16x16x32_bf16 v[28:31], v[160:163], v[220:223], v[28:31]
	v_mfma_f32_16x16x32_bf16 v[24:27], v[176:179], v[220:223], v[24:27]
	v_mfma_f32_16x16x32_bf16 v[12:15], v[160:163], v[228:231], v[12:15]
	v_mfma_f32_16x16x32_bf16 v[8:11], v[176:179], v[228:231], v[8:11]
	s_setprio 0
	s_setprio 1
	v_mfma_f32_16x16x32_bf16 v[52:55], v[180:183], v[198:201], v[52:55]
	v_mfma_f32_16x16x32_bf16 v[48:51], v[190:193], v[198:201], v[48:51]
	v_mfma_f32_16x16x32_bf16 v[36:39], v[180:183], v[208:211], v[36:39]
	v_mfma_f32_16x16x32_bf16 v[32:35], v[190:193], v[208:211], v[32:35]
	v_mfma_f32_16x16x32_bf16 v[20:23], v[180:183], v[216:219], v[20:23]
	v_mfma_f32_16x16x32_bf16 v[16:19], v[190:193], v[216:219], v[16:19]
	v_mfma_f32_16x16x32_bf16 v[4:7], v[180:183], v[224:227], v[4:7]
	v_mfma_f32_16x16x32_bf16 v[0:3], v[190:193], v[224:227], v[0:3]
	v_mfma_f32_16x16x32_bf16 v[52:55], v[184:187], v[202:205], v[52:55]
	v_mfma_f32_16x16x32_bf16 v[48:51], v[194:197], v[202:205], v[48:51]
	v_mfma_f32_16x16x32_bf16 v[36:39], v[184:187], v[212:215], v[36:39]
	v_mfma_f32_16x16x32_bf16 v[32:35], v[194:197], v[212:215], v[32:35]
	v_mfma_f32_16x16x32_bf16 v[20:23], v[184:187], v[220:223], v[20:23]
	v_mfma_f32_16x16x32_bf16 v[16:19], v[194:197], v[220:223], v[16:19]
	v_mfma_f32_16x16x32_bf16 v[4:7], v[184:187], v[228:231], v[4:7]
	v_mfma_f32_16x16x32_bf16 v[0:3], v[194:197], v[228:231], v[0:3]
	s_setprio 0
	s_add_i32 s65, s65, 2
	s_add_u32 s10, s10, 0x100
	s_addc_u32 s11, s11, 0
	s_add_u32 s60, s60, 0x100
	s_addc_u32 s61, s61, 0
	s_cmp_gt_u32 s65, 29
	s_barrier
	s_cbranch_scc0 .LBB0_136
	s_and_b64 vcc, exec, s[84:85]
	s_cbranch_vccz .LBB0_139
	s_barrier

; #define PG8_STAGE(bufoff, gbase, voff) do { _Pragma("unroll") for (int _i = 0; _i < 2; ++_i) \
;         __builtin_amdgcn_global_load_lds((const unsigned*)((const char*)(gbase) + (voff)[_i]), (PG8_LAS unsigned*)(lds + (bufoff) + ldsw + _i * 8192), 16, 0, 0); } while (0)
; #define PG8_LDA(dst, b, h) do { _Pragma("unroll") for (int m = 0; m < 4; ++m) _Pragma("unroll") for (int k = 0; k < 2; ++k) dst[m][k] = *(const PG8_LAS bf16x8*)(lds + PG8_SA(b, h) + aoff + m * 2048 + k * 1024); } while (0)
; #define PG8_LDB(dst, b, h) do { _Pragma("unroll") for (int n = 0; n < 2; ++n) _Pragma("unroll") for (int k = 0; k < 2; ++k) dst[n][k] = *(const PG8_LAS bf16x8*)(lds + PG8_SB(b, h) + boff + n * 2048 + k * 1024); } while (0)
; #define PG8_MMA(ai, bj, At, Bt) do { __builtin_amdgcn_s_setprio(1); _Pragma("unroll") for (int m = 0; m < 4; ++m) _Pragma("unroll") for (int n = 0; n < 2; ++n) _Pragma("unroll") for (int k = 0; k < 2; ++k) \
;         acc[ai][bj][m][n] = __builtin_amdgcn_mfma_f32_16x16x32_bf16(Bt[n][k], At[m][k], acc[ai][bj][m][n], 0, 0, 0); __builtin_amdgcn_s_setprio(0); } while (0)
; #define PG8_BAR __builtin_amdgcn_s_barrier()
; template <class Epi, bool BLKDIAG = false>
; __device__ __forceinline__ void gemm_phase(PG8_LAS unsigned char* lds, const Gemm g, const StaticOrder& S, const Epi& E) {
;     ...
;             const char* a1 = cA + (size_t)(t + 1) * kstep;
;             const char* a2 = last ? nA : cA + (size_t)(t + 2) * kstep; const char* b2 = last ? nB : cB + (size_t)(t + 2) * kstep;
;             const char* a3 = a2 + kstep; const char* b3 = b2 + kstep;
;             PG8_LDB(B0, 0, 0); PG8_LDB(B1, 0, 1); PG8_SCHED; PG8_LDA(At, 0, 0); PG8_STAGE(PG8_SA(1, 1), a1 + hstepA, voffA);
;             PG8_WAIT_V(8); PG8_WAIT_L(0); PG8_BAR; if (lo_) PG8_MMA(0, 0, At, B0); if (hi_) PG8_MMA(0, 1, At, B1); PG8_BAR; PG8_SCHED;
;             PG8_LDA(At, 0, 1); PG8_STAGE(PG8_SB(0, 0), b2, voffB); PG8_STAGE(PG8_SB(0, 1), b2 + hstepB, voffB); PG8_STAGE(PG8_SA(0, 0), a2, voffA);
;             PG8_WAIT_V(8); PG8_WAIT_L(0); PG8_BAR; if (lo_) PG8_MMA(1, 0, At, B0); if (hi_) PG8_MMA(1, 1, At, B1); PG8_BAR; PG8_SCHED;
;             PG8_LDB(B0, 1, 0); PG8_LDB(B1, 1, 1); PG8_SCHED; PG8_LDA(At, 1, 0); PG8_STAGE(PG8_SA(0, 1), a2 + hstepA, voffA);
;             PG8_WAIT_V(8); PG8_WAIT_L(0); PG8_BAR; if (lo_) PG8_MMA(0, 0, At, B0); if (hi_) PG8_MMA(0, 1, At, B1); PG8_BAR; PG8_SCHED;
.LBB0_963:
	s_add_u32 s44, s60, 0xfff00080
	s_addc_u32 s45, s61, -1
	s_cmp_eq_u32 s92, 4
	s_cselect_b32 s57, s41, s45
	s_cselect_b32 s56, s86, s44
	s_cselect_b32 s45, s23, s91
	s_cselect_b32 s44, s87, s90
	s_add_i32 s93, 0, 0x14000
	v_add_u32_e32 v180, s93, v208
	ds_read_b128 v[168:171], v180
	ds_read_b128 v[172:175], v180 offset:1024
	ds_read_b128 v[176:179], v180 offset:2048
	ds_read_b128 v[180:183], v180 offset:3072
	s_mov_b32 m0, s88
	v_lshl_add_u64 v[240:241], s[60:61], 0, v[198:199]
	ds_read_b128 v[184:187], v209
	ds_read_b128 v[212:215], v209 offset:1024
	ds_read_b128 v[216:219], v209 offset:2048
	ds_read_b128 v[220:223], v209 offset:3072
	ds_read_b128 v[224:227], v209 offset:4096
	ds_read_b128 v[228:231], v209 offset:5120
	ds_read_b128 v[232:235], v209 offset:6144
	ds_read_b128 v[236:239], v209 offset:7168
	global_load_lds_dwordx4 v[240:241], off
	v_lshl_add_u64 v[240:241], s[60:61], 0, v[200:201]
	s_mov_b32 m0, s89
	s_nop 0
	global_load_lds_dwordx4 v[240:241], off
	s_waitcnt vmcnt(8)
	s_waitcnt lgkmcnt(0)
	s_barrier
	s_setprio 1
	s_waitcnt lgkmcnt(0)
	v_mfma_f32_16x16x32_bf16 v[164:167], v[168:171], v[184:187], v[164:167]
	v_mfma_f32_16x16x32_bf16 v[160:163], v[176:179], v[184:187], v[160:163]
	v_mfma_f32_16x16x32_bf16 v[124:127], v[168:171], v[216:219], v[124:127]
	v_mfma_f32_16x16x32_bf16 v[120:123], v[176:179], v[216:219], v[120:123]
	v_mfma_f32_16x16x32_bf16 v[44:47], v[168:171], v[224:227], v[44:47]
	v_mfma_f32_16x16x32_bf16 v[40:43], v[176:179], v[224:227], v[40:43]
	v_mfma_f32_16x16x32_bf16 v[36:39], v[168:171], v[232:235], v[36:39]
	v_mfma_f32_16x16x32_bf16 v[32:35], v[176:179], v[232:235], v[32:35]
	v_mfma_f32_16x16x32_bf16 v[164:167], v[172:175], v[212:215], v[164:167]
	v_mfma_f32_16x16x32_bf16 v[160:163], v[180:183], v[212:215], v[160:163]
	v_mfma_f32_16x16x32_bf16 v[124:127], v[172:175], v[220:223], v[124:127]
	v_mfma_f32_16x16x32_bf16 v[120:123], v[180:183], v[220:223], v[120:123]
	v_mfma_f32_16x16x32_bf16 v[44:47], v[172:175], v[228:231], v[44:47]
	v_mfma_f32_16x16x32_bf16 v[40:43], v[180:183], v[228:231], v[40:43]
	v_mfma_f32_16x16x32_bf16 v[36:39], v[172:175], v[236:239], v[36:39]
	v_mfma_f32_16x16x32_bf16 v[32:35], v[180:183], v[236:239], v[32:35]
	s_setprio 0
	s_barrier
	s_mov_b32 m0, s51
	v_lshl_add_u64 v[240:241], s[44:45], 0, v[192:193]
	s_add_u32 s94, s44, 0x20000
	ds_read_b128 v[184:187], v209 offset:16384
	ds_read_b128 v[212:215], v209 offset:17408
	ds_read_b128 v[216:219], v209 offset:18432
	ds_read_b128 v[220:223], v209 offset:19456
	ds_read_b128 v[224:227], v209 offset:20480
	ds_read_b128 v[228:231], v209 offset:21504
	ds_read_b128 v[232:235], v209 offset:22528
	ds_read_b128 v[236:239], v209 offset:23552
	global_load_lds_dwordx4 v[240:241], off
	v_lshl_add_u64 v[242:243], s[44:45], 0, v[196:197]
	s_mov_b32 m0, s62
	s_addc_u32 s95, s45, 0
	s_add_i32 s93, s93, s33
	global_load_lds_dwordx4 v[242:243], off
	v_lshl_add_u64 v[244:245], s[94:95], 0, v[192:193]
	s_mov_b32 m0, s93
	v_lshl_add_u64 v[246:247], s[56:57], 0, v[194:195]
	global_load_lds_dwordx4 v[244:245], off
	v_lshl_add_u64 v[244:245], s[94:95], 0, v[196:197]
	s_add_i32 m0, s93, 0x2000
	s_nop 0
	global_load_lds_dwordx4 v[244:245], off
	v_lshl_add_u64 v[244:245], s[56:57], 0, v[190:191]
	s_mov_b32 m0, s35
	s_nop 0
	global_load_lds_dwordx4 v[244:245], off
	s_mov_b32 m0, s65
	s_nop 0
	global_load_lds_dwordx4 v[246:247], off
	s_waitcnt vmcnt(8)
	s_waitcnt lgkmcnt(0)
	s_barrier
	s_setprio 1
	s_waitcnt lgkmcnt(0)
	v_mfma_f32_16x16x32_bf16 v[28:31], v[168:171], v[184:187], v[28:31]
	v_mfma_f32_16x16x32_bf16 v[24:27], v[176:179], v[184:187], v[24:27]
	v_mfma_f32_16x16x32_bf16 v[20:23], v[168:171], v[216:219], v[20:23]
	v_mfma_f32_16x16x32_bf16 v[16:19], v[176:179], v[216:219], v[16:19]
	v_mfma_f32_16x16x32_bf16 v[12:15], v[168:171], v[224:227], v[12:15]
	v_mfma_f32_16x16x32_bf16 v[8:11], v[176:179], v[224:227], v[8:11]
	v_mfma_f32_16x16x32_bf16 v[4:7], v[168:171], v[232:235], v[4:7]
	v_mfma_f32_16x16x32_bf16 v[0:3], v[176:179], v[232:235], v[0:3]
	v_mfma_f32_16x16x32_bf16 v[28:31], v[172:175], v[212:215], v[28:31]
	v_mfma_f32_16x16x32_bf16 v[24:27], v[180:183], v[212:215], v[24:27]
	v_mfma_f32_16x16x32_bf16 v[20:23], v[172:175], v[220:223], v[20:23]
	v_mfma_f32_16x16x32_bf16 v[16:19], v[180:183], v[220:223], v[16:19]
	v_mfma_f32_16x16x32_bf16 v[12:15], v[172:175], v[228:231], v[12:15]
	v_mfma_f32_16x16x32_bf16 v[8:11], v[180:183], v[228:231], v[8:11]
	v_mfma_f32_16x16x32_bf16 v[4:7], v[172:175], v[236:239], v[4:7]
	v_mfma_f32_16x16x32_bf16 v[0:3], v[180:183], v[236:239], v[0:3]
	s_setprio 0
	s_barrier
	s_add_i32 s93, 0, 0x1c000
	v_add_u32_e32 v180, s93, v208
	ds_read_b128 v[168:171], v180
	ds_read_b128 v[172:175], v180 offset:1024
	ds_read_b128 v[176:179], v180 offset:2048
	ds_read_b128 v[180:183], v180 offset:3072
	s_add_u32 s56, s56, 0x100000
	s_addc_u32 s57, s57, 0
	s_mov_b32 m0, s70
	v_lshl_add_u64 v[248:249], s[56:57], 0, v[190:191]
	ds_read_b128 v[184:187], v209 offset:32768
	ds_read_b128 v[212:215], v209 offset:33792
	ds_read_b128 v[216:219], v209 offset:34816
	ds_read_b128 v[220:223], v209 offset:35840
	ds_read_b128 v[224:227], v209 offset:36864
	ds_read_b128 v[228:231], v209 offset:37888
	ds_read_b128 v[232:235], v209 offset:38912
	ds_read_b128 v[236:239], v209 offset:39936
	global_load_lds_dwordx4 v[248:249], off
	v_lshl_add_u64 v[248:249], s[56:57], 0, v[194:195]
	s_mov_b32 m0, s71
	s_nop 0
	global_load_lds_dwordx4 v[248:249], off
	s_waitcnt vmcnt(8)
	s_waitcnt lgkmcnt(0)
	s_barrier
; #define PG8_STAGE(bufoff, gbase, voff) do { _Pragma("unroll") for (int _i = 0; _i < 2; ++_i) \
;         __builtin_amdgcn_global_load_lds((const unsigned*)((const char*)(gbase) + (voff)[_i]), (PG8_LAS unsigned*)(lds + (bufoff) + ldsw + _i * 8192), 16, 0, 0); } while (0)
; #define PG8_LDA(dst, b, h) do { _Pragma("unroll") for (int m = 0; m < 4; ++m) _Pragma("unroll") for (int k = 0; k < 2; ++k) dst[m][k] = *(const PG8_LAS bf16x8*)(lds + PG8_SA(b, h) + aoff + m * 2048 + k * 1024); } while (0)
; #define PG8_MMA(ai, bj, At, Bt) do { __builtin_amdgcn_s_setprio(1); _Pragma("unroll") for (int m = 0; m < 4; ++m) _Pragma("unroll") for (int n = 0; n < 2; ++n) _Pragma("unroll") for (int k = 0; k < 2; ++k) \
;         acc[ai][bj][m][n] = __builtin_amdgcn_mfma_f32_16x16x32_bf16(Bt[n][k], At[m][k], acc[ai][bj][m][n], 0, 0, 0); __builtin_amdgcn_s_setprio(0); } while (0)
; #define PG8_WAIT_V(n) asm volatile("s_waitcnt vmcnt(" #n ")" ::: "memory")
; #define PG8_WAIT_L(n) asm volatile("s_waitcnt lgkmcnt(" #n ")" ::: "memory")
; #define PG8_BAR __builtin_amdgcn_s_barrier()
; #define PG8_SCHED __builtin_amdgcn_sched_barrier(0)
; template <class Epi, bool BLKDIAG = false>
; __device__ __forceinline__ void gemm_phase(PG8_LAS unsigned char* lds, const Gemm g, const StaticOrder& S, const Epi& E) {
;     ...
;             PG8_LDA(At, 1, 1); PG8_STAGE(PG8_SB(1, 0), b3, voffB); PG8_STAGE(PG8_SB(1, 1), b3 + hstepB, voffB); PG8_STAGE(PG8_SA(1, 0), a3, voffA);
;             PG8_WAIT_V(8); PG8_WAIT_L(0); PG8_BAR; if (lo_) PG8_MMA(1, 0, At, B0); if (hi_) PG8_MMA(1, 1, At, B1); PG8_BAR; PG8_SCHED;
;         }
;         if (wr == 0) PG8_BAR;
	s_setprio 1
	s_waitcnt lgkmcnt(0)
	v_mfma_f32_16x16x32_bf16 v[164:167], v[168:171], v[184:187], v[164:167]
	v_mfma_f32_16x16x32_bf16 v[160:163], v[176:179], v[184:187], v[160:163]
	v_mfma_f32_16x16x32_bf16 v[124:127], v[168:171], v[216:219], v[124:127]
	v_mfma_f32_16x16x32_bf16 v[120:123], v[176:179], v[216:219], v[120:123]
	v_mfma_f32_16x16x32_bf16 v[44:47], v[168:171], v[224:227], v[44:47]
	v_mfma_f32_16x16x32_bf16 v[40:43], v[176:179], v[224:227], v[40:43]
	v_mfma_f32_16x16x32_bf16 v[36:39], v[168:171], v[232:235], v[36:39]
	v_mfma_f32_16x16x32_bf16 v[32:35], v[176:179], v[232:235], v[32:35]
	v_mfma_f32_16x16x32_bf16 v[164:167], v[172:175], v[212:215], v[164:167]
	v_mfma_f32_16x16x32_bf16 v[160:163], v[180:183], v[212:215], v[160:163]
	v_mfma_f32_16x16x32_bf16 v[124:127], v[172:175], v[220:223], v[124:127]
	v_mfma_f32_16x16x32_bf16 v[120:123], v[180:183], v[220:223], v[120:123]
	v_mfma_f32_16x16x32_bf16 v[44:47], v[172:175], v[228:231], v[44:47]
	v_mfma_f32_16x16x32_bf16 v[40:43], v[180:183], v[228:231], v[40:43]
	v_mfma_f32_16x16x32_bf16 v[36:39], v[172:175], v[236:239], v[36:39]
	v_mfma_f32_16x16x32_bf16 v[32:35], v[180:183], v[236:239], v[32:35]
	s_setprio 0
	s_barrier
	s_mov_b32 m0, s73
	v_lshl_add_u64 v[240:241], v[240:241], 0, s[8:9]
	s_add_u32 s44, s44, 0x20080
	ds_read_b128 v[184:187], v209 offset:49152
	ds_read_b128 v[212:215], v209 offset:50176
	ds_read_b128 v[216:219], v209 offset:51200
	ds_read_b128 v[220:223], v209 offset:52224
	ds_read_b128 v[224:227], v209 offset:53248
	ds_read_b128 v[228:231], v209 offset:54272
	ds_read_b128 v[232:235], v209 offset:55296
	ds_read_b128 v[236:239], v209 offset:56320
	global_load_lds_dwordx4 v[240:241], off
	v_lshl_add_u64 v[240:241], v[242:243], 0, s[8:9]
	s_mov_b32 m0, s74
	s_addc_u32 s45, s45, 0
	s_add_i32 s56, s93, s33
	global_load_lds_dwordx4 v[240:241], off
	v_lshl_add_u64 v[240:241], s[44:45], 0, v[192:193]
	s_mov_b32 m0, s56
	s_nop 0
	global_load_lds_dwordx4 v[240:241], off
	v_lshl_add_u64 v[240:241], s[44:45], 0, v[196:197]
	s_add_i32 m0, s56, 0x2000
	s_nop 0
	global_load_lds_dwordx4 v[240:241], off
	v_lshl_add_u64 v[240:241], v[244:245], 0, s[8:9]
	s_mov_b32 m0, s75
	s_nop 0
	global_load_lds_dwordx4 v[240:241], off
	v_lshl_add_u64 v[240:241], v[246:247], 0, s[8:9]
	s_mov_b32 m0, s78
	s_nop 0
	global_load_lds_dwordx4 v[240:241], off
	s_waitcnt vmcnt(8)
	s_waitcnt lgkmcnt(0)
	s_barrier
	s_setprio 1
	s_waitcnt lgkmcnt(0)
	v_mfma_f32_16x16x32_bf16 v[28:31], v[168:171], v[184:187], v[28:31]
	v_mfma_f32_16x16x32_bf16 v[24:27], v[176:179], v[184:187], v[24:27]
	v_mfma_f32_16x16x32_bf16 v[20:23], v[168:171], v[216:219], v[20:23]
	v_mfma_f32_16x16x32_bf16 v[16:19], v[176:179], v[216:219], v[16:19]
	v_mfma_f32_16x16x32_bf16 v[12:15], v[168:171], v[224:227], v[12:15]
	v_mfma_f32_16x16x32_bf16 v[8:11], v[176:179], v[224:227], v[8:11]
	v_mfma_f32_16x16x32_bf16 v[4:7], v[168:171], v[232:235], v[4:7]
	v_mfma_f32_16x16x32_bf16 v[0:3], v[176:179], v[232:235], v[0:3]
	v_mfma_f32_16x16x32_bf16 v[28:31], v[172:175], v[212:215], v[28:31]
	v_mfma_f32_16x16x32_bf16 v[24:27], v[180:183], v[212:215], v[24:27]
	v_mfma_f32_16x16x32_bf16 v[20:23], v[172:175], v[220:223], v[20:23]
	v_mfma_f32_16x16x32_bf16 v[16:19], v[180:183], v[220:223], v[16:19]
	v_mfma_f32_16x16x32_bf16 v[12:15], v[172:175], v[228:231], v[12:15]
	v_mfma_f32_16x16x32_bf16 v[8:11], v[180:183], v[228:231], v[8:11]
	v_mfma_f32_16x16x32_bf16 v[4:7], v[172:175], v[236:239], v[4:7]
	v_mfma_f32_16x16x32_bf16 v[0:3], v[180:183], v[236:239], v[0:3]
	s_setprio 0
	s_add_i32 s92, s92, 2
	s_add_u32 s60, s60, 0x100
	s_addc_u32 s61, s61, 0
	s_add_u32 s90, s90, 0x100
	s_addc_u32 s91, s91, 0
	s_cmp_gt_u32 s92, 5
	s_barrier
	s_cbranch_scc0 .LBB0_963
	v_mfma_f32_16x16x32_bf16 v[184:187], v[52:55], v[56:59], v[72:75]
	s_and_b64 vcc, exec, s[10:11]
	v_mfma_f32_16x16x32_bf16 v[180:183], v[48:51], v[56:59], v[76:79]
	v_mfma_f32_16x16x32_bf16 v[176:179], v[52:55], v[60:63], v[80:83]
	v_mfma_f32_16x16x32_bf16 v[172:175], v[48:51], v[60:63], v[84:87]
	v_mfma_f32_16x16x32_bf16 v[168:171], v[52:55], v[64:67], v[88:91]
	v_mfma_f32_16x16x32_bf16 v[88:91], v[48:51], v[64:67], v[92:95]
	v_mfma_f32_16x16x32_bf16 v[84:87], v[52:55], v[68:71], v[96:99]
	v_mfma_f32_16x16x32_bf16 v[80:83], v[48:51], v[68:71], v[100:103]
	v_mfma_f32_16x16x32_bf16 v[76:79], v[52:55], v[108:111], v[132:135]
	v_mfma_f32_16x16x32_bf16 v[72:75], v[48:51], v[108:111], v[136:139]
	v_mfma_f32_16x16x32_bf16 v[68:71], v[52:55], v[112:115], v[140:143]
	v_mfma_f32_16x16x32_bf16 v[64:67], v[48:51], v[112:115], v[144:147]
	v_mfma_f32_16x16x32_bf16 v[60:63], v[52:55], v[116:119], v[148:151]
	v_mfma_f32_16x16x32_bf16 v[56:59], v[48:51], v[116:119], v[152:155]
	v_mfma_f32_16x16x32_bf16 v[52:55], v[52:55], v[104:107], v[156:159]
	v_mfma_f32_16x16x32_bf16 v[48:51], v[48:51], v[104:107], v[128:131]
	s_cbranch_vccz .LBB0_966
	s_barrier

; #define PG8_STAGE(bufoff, gbase, voff) do { _Pragma("unroll") for (int _i = 0; _i < 2; ++_i) \
;         __builtin_amdgcn_global_load_lds((const unsigned*)((const char*)(gbase) + (voff)[_i]), (PG8_LAS unsigned*)(lds + (bufoff) + ldsw + _i * 8192), 16, 0, 0); } while (0)
; #define PG8_LDA(dst, b, h) do { _Pragma("unroll") for (int m = 0; m < 4; ++m) _Pragma("unroll") for (int k = 0; k < 2; ++k) dst[m][k] = *(const PG8_LAS bf16x8*)(lds + PG8_SA(b, h) + aoff + m * 2048 + k * 1024); } while (0)
; #define PG8_LDB(dst, b, h) do { _Pragma("unroll") for (int n = 0; n < 2; ++n) _Pragma("unroll") for (int k = 0; k < 2; ++k) dst[n][k] = *(const PG8_LAS bf16x8*)(lds + PG8_SB(b, h) + boff + n * 2048 + k * 1024); } while (0)
; #define PG8_MMA(ai, bj, At, Bt) do { __builtin_amdgcn_s_setprio(1); _Pragma("unroll") for (int m = 0; m < 4; ++m) _Pragma("unroll") for (int n = 0; n < 2; ++n) _Pragma("unroll") for (int k = 0; k < 2; ++k) \
;         acc[ai][bj][m][n] = __builtin_amdgcn_mfma_f32_16x16x32_bf16(Bt[n][k], At[m][k], acc[ai][bj][m][n], 0, 0, 0); __builtin_amdgcn_s_setprio(0); } while (0)
; #define PG8_WAIT_V(n) asm volatile("s_waitcnt vmcnt(" #n ")" ::: "memory")
; #define PG8_WAIT_L(n) asm volatile("s_waitcnt lgkmcnt(" #n ")" ::: "memory")
; #define PG8_BAR __builtin_amdgcn_s_barrier()
; #define PG8_SCHED __builtin_amdgcn_sched_barrier(0)
; template <class Epi, bool BLKDIAG = false>
; __device__ __forceinline__ void gemm_phase(PG8_LAS unsigned char* lds, const Gemm g, const StaticOrder& S, const Epi& E) {
;     ...
;             const char* a1 = cA + (size_t)(t + 1) * kstep;
;             const char* a2 = last ? nA : cA + (size_t)(t + 2) * kstep; const char* b2 = last ? nB : cB + (size_t)(t + 2) * kstep;
;             const char* a3 = a2 + kstep; const char* b3 = b2 + kstep;
;             PG8_LDB(B0, 0, 0); PG8_LDB(B1, 0, 1); PG8_SCHED; PG8_LDA(At, 0, 0); PG8_STAGE(PG8_SA(1, 1), a1 + hstepA, voffA);
;             PG8_WAIT_V(8); PG8_WAIT_L(0); PG8_BAR; if (lo_) PG8_MMA(0, 0, At, B0); if (hi_) PG8_MMA(0, 1, At, B1); PG8_BAR; PG8_SCHED;
;             PG8_LDA(At, 0, 1); PG8_STAGE(PG8_SB(0, 0), b2, voffB); PG8_STAGE(PG8_SB(0, 1), b2 + hstepB, voffB); PG8_STAGE(PG8_SA(0, 0), a2, voffA);
;             PG8_WAIT_V(8); PG8_WAIT_L(0); PG8_BAR; if (lo_) PG8_MMA(1, 0, At, B0); if (hi_) PG8_MMA(1, 1, At, B1); PG8_BAR; PG8_SCHED;
.LBB0_1000:
	ds_read_b128 v[144:147], v161
	ds_read_b128 v[164:167], v161 offset:1024
	ds_read_b128 v[168:171], v161 offset:2048
	ds_read_b128 v[172:175], v161 offset:3072
	ds_read_b128 v[176:179], v162
	ds_read_b128 v[180:183], v162 offset:1024
	ds_read_b128 v[184:187], v162 offset:2048
	ds_read_b128 v[190:193], v162 offset:3072
	s_add_u32 s72, s70, 0xfff80080
	s_addc_u32 s73, s71, -1
	s_cmp_eq_u32 s85, 28
	s_cselect_b32 s75, s51, s73
	s_cselect_b32 s74, s81, s72
	s_cselect_b32 s73, s49, s84
	s_cselect_b32 s72, s82, s83
	v_lshl_add_u64 v[148:149], s[70:71], 0, v[136:137]
	s_add_i32 m0, s35, 0xc000
	ds_read_b128 v[194:197], v163
	ds_read_b128 v[198:201], v163 offset:1024
	ds_read_b128 v[202:205], v163 offset:2048
	ds_read_b128 v[208:211], v163 offset:3072
	ds_read_b128 v[212:215], v163 offset:4096
	ds_read_b128 v[216:219], v163 offset:5120
	ds_read_b128 v[220:223], v163 offset:6144
	ds_read_b128 v[224:227], v163 offset:7168
	global_load_lds_dwordx4 v[148:149], off
	v_lshl_add_u64 v[148:149], s[70:71], 0, v[138:139]
	s_add_i32 m0, s35, 0xe000
	s_nop 0
	global_load_lds_dwordx4 v[148:149], off
	s_waitcnt vmcnt(8)
	s_waitcnt lgkmcnt(0)
	s_barrier
	s_setprio 1
	s_waitcnt lgkmcnt(0)
	v_mfma_f32_16x16x32_bf16 v[124:127], v[144:147], v[194:197], v[124:127]
	v_mfma_f32_16x16x32_bf16 v[120:123], v[168:171], v[194:197], v[120:123]
	v_mfma_f32_16x16x32_bf16 v[108:111], v[144:147], v[202:205], v[108:111]
	v_mfma_f32_16x16x32_bf16 v[104:107], v[168:171], v[202:205], v[104:107]
	v_mfma_f32_16x16x32_bf16 v[92:95], v[144:147], v[212:215], v[92:95]
	v_mfma_f32_16x16x32_bf16 v[88:91], v[168:171], v[212:215], v[88:91]
	v_mfma_f32_16x16x32_bf16 v[76:79], v[144:147], v[220:223], v[76:79]
	v_mfma_f32_16x16x32_bf16 v[72:75], v[168:171], v[220:223], v[72:75]
	v_mfma_f32_16x16x32_bf16 v[124:127], v[164:167], v[198:201], v[124:127]
	v_mfma_f32_16x16x32_bf16 v[120:123], v[172:175], v[198:201], v[120:123]
	v_mfma_f32_16x16x32_bf16 v[108:111], v[164:167], v[208:211], v[108:111]
	v_mfma_f32_16x16x32_bf16 v[104:107], v[172:175], v[208:211], v[104:107]
	v_mfma_f32_16x16x32_bf16 v[92:95], v[164:167], v[216:219], v[92:95]
	v_mfma_f32_16x16x32_bf16 v[88:91], v[172:175], v[216:219], v[88:91]
	v_mfma_f32_16x16x32_bf16 v[76:79], v[164:167], v[224:227], v[76:79]
	v_mfma_f32_16x16x32_bf16 v[72:75], v[172:175], v[224:227], v[72:75]
	s_setprio 0
	s_setprio 1
	v_mfma_f32_16x16x32_bf16 v[116:119], v[176:179], v[194:197], v[116:119]
	v_mfma_f32_16x16x32_bf16 v[112:115], v[184:187], v[194:197], v[112:115]
	v_mfma_f32_16x16x32_bf16 v[100:103], v[176:179], v[202:205], v[100:103]
	v_mfma_f32_16x16x32_bf16 v[96:99], v[184:187], v[202:205], v[96:99]
	v_mfma_f32_16x16x32_bf16 v[84:87], v[176:179], v[212:215], v[84:87]
	v_mfma_f32_16x16x32_bf16 v[80:83], v[184:187], v[212:215], v[80:83]
	v_mfma_f32_16x16x32_bf16 v[68:71], v[176:179], v[220:223], v[68:71]
	v_mfma_f32_16x16x32_bf16 v[64:67], v[184:187], v[220:223], v[64:67]
	v_mfma_f32_16x16x32_bf16 v[116:119], v[180:183], v[198:201], v[116:119]
	v_mfma_f32_16x16x32_bf16 v[112:115], v[190:193], v[198:201], v[112:115]
	v_mfma_f32_16x16x32_bf16 v[100:103], v[180:183], v[208:211], v[100:103]
	v_mfma_f32_16x16x32_bf16 v[96:99], v[190:193], v[208:211], v[96:99]
	v_mfma_f32_16x16x32_bf16 v[84:87], v[180:183], v[216:219], v[84:87]
	v_mfma_f32_16x16x32_bf16 v[80:83], v[190:193], v[216:219], v[80:83]
	v_mfma_f32_16x16x32_bf16 v[68:71], v[180:183], v[224:227], v[68:71]
	v_mfma_f32_16x16x32_bf16 v[64:67], v[190:193], v[224:227], v[64:67]
	s_setprio 0
	s_barrier
	s_add_i32 s86, s78, s33
	v_lshl_add_u64 v[148:149], s[72:73], 0, v[130:131]
	s_mov_b32 m0, s86
	ds_read_b128 v[194:197], v163 offset:16384
	ds_read_b128 v[198:201], v163 offset:17408
	ds_read_b128 v[202:205], v163 offset:18432
	ds_read_b128 v[208:211], v163 offset:19456
	ds_read_b128 v[212:215], v163 offset:20480
	ds_read_b128 v[216:219], v163 offset:21504
	ds_read_b128 v[220:223], v163 offset:22528
	ds_read_b128 v[224:227], v163 offset:23552
	global_load_lds_dwordx4 v[148:149], off
	s_add_i32 m0, s86, 0x2000
	s_add_u32 s86, s72, 0x80000
	v_lshl_add_u64 v[228:229], s[72:73], 0, v[134:135]
	s_addc_u32 s87, s73, 0
	s_add_i32 s88, s79, s33
	global_load_lds_dwordx4 v[228:229], off
	v_lshl_add_u64 v[230:231], s[86:87], 0, v[130:131]
	s_mov_b32 m0, s88
	v_lshl_add_u64 v[232:233], s[74:75], 0, v[132:133]
	global_load_lds_dwordx4 v[230:231], off
	v_lshl_add_u64 v[230:231], s[86:87], 0, v[134:135]
	s_add_i32 m0, s88, 0x2000
	s_nop 0
	global_load_lds_dwordx4 v[230:231], off
	v_lshl_add_u64 v[230:231], s[74:75], 0, v[128:129]
	s_mov_b32 m0, s35
	s_nop 0
	global_load_lds_dwordx4 v[230:231], off
	s_mov_b32 m0, s62
	s_nop 0
	global_load_lds_dwordx4 v[232:233], off
	s_waitcnt vmcnt(8)
	s_waitcnt lgkmcnt(0)
	s_barrier
; #define PG8_STAGE(bufoff, gbase, voff) do { _Pragma("unroll") for (int _i = 0; _i < 2; ++_i) \
;         __builtin_amdgcn_global_load_lds((const unsigned*)((const char*)(gbase) + (voff)[_i]), (PG8_LAS unsigned*)(lds + (bufoff) + ldsw + _i * 8192), 16, 0, 0); } while (0)
; #define PG8_LDA(dst, b, h) do { _Pragma("unroll") for (int m = 0; m < 4; ++m) _Pragma("unroll") for (int k = 0; k < 2; ++k) dst[m][k] = *(const PG8_LAS bf16x8*)(lds + PG8_SA(b, h) + aoff + m * 2048 + k * 1024); } while (0)
; #define PG8_LDB(dst, b, h) do { _Pragma("unroll") for (int n = 0; n < 2; ++n) _Pragma("unroll") for (int k = 0; k < 2; ++k) dst[n][k] = *(const PG8_LAS bf16x8*)(lds + PG8_SB(b, h) + boff + n * 2048 + k * 1024); } while (0)
; #define PG8_MMA(ai, bj, At, Bt) do { __builtin_amdgcn_s_setprio(1); _Pragma("unroll") for (int m = 0; m < 4; ++m) _Pragma("unroll") for (int n = 0; n < 2; ++n) _Pragma("unroll") for (int k = 0; k < 2; ++k) \
;         acc[ai][bj][m][n] = __builtin_amdgcn_mfma_f32_16x16x32_bf16(Bt[n][k], At[m][k], acc[ai][bj][m][n], 0, 0, 0); __builtin_amdgcn_s_setprio(0); } while (0)
; #define PG8_WAIT_V(n) asm volatile("s_waitcnt vmcnt(" #n ")" ::: "memory")
; #define PG8_WAIT_L(n) asm volatile("s_waitcnt lgkmcnt(" #n ")" ::: "memory")
; #define PG8_BAR __builtin_amdgcn_s_barrier()
; #define PG8_SCHED __builtin_amdgcn_sched_barrier(0)
; template <class Epi, bool BLKDIAG = false>
; __device__ __forceinline__ void gemm_phase(PG8_LAS unsigned char* lds, const Gemm g, const StaticOrder& S, const Epi& E) {
;     ...
;             PG8_WAIT_V(8); PG8_WAIT_L(0); PG8_BAR; if (lo_) PG8_MMA(1, 0, At, B0); if (hi_) PG8_MMA(1, 1, At, B1); PG8_BAR; PG8_SCHED;
;             PG8_LDB(B0, 1, 0); PG8_LDB(B1, 1, 1); PG8_SCHED; PG8_LDA(At, 1, 0); PG8_STAGE(PG8_SA(0, 1), a2 + hstepA, voffA);
;             PG8_WAIT_V(8); PG8_WAIT_L(0); PG8_BAR; if (lo_) PG8_MMA(0, 0, At, B0); if (hi_) PG8_MMA(0, 1, At, B1); PG8_BAR; PG8_SCHED;
	s_setprio 1
	s_waitcnt lgkmcnt(0)
	v_mfma_f32_16x16x32_bf16 v[60:63], v[144:147], v[194:197], v[60:63]
	v_mfma_f32_16x16x32_bf16 v[56:59], v[168:171], v[194:197], v[56:59]
	v_mfma_f32_16x16x32_bf16 v[44:47], v[144:147], v[202:205], v[44:47]
	v_mfma_f32_16x16x32_bf16 v[40:43], v[168:171], v[202:205], v[40:43]
	v_mfma_f32_16x16x32_bf16 v[28:31], v[144:147], v[212:215], v[28:31]
	v_mfma_f32_16x16x32_bf16 v[24:27], v[168:171], v[212:215], v[24:27]
	v_mfma_f32_16x16x32_bf16 v[12:15], v[144:147], v[220:223], v[12:15]
	v_mfma_f32_16x16x32_bf16 v[8:11], v[168:171], v[220:223], v[8:11]
	v_mfma_f32_16x16x32_bf16 v[60:63], v[164:167], v[198:201], v[60:63]
	v_mfma_f32_16x16x32_bf16 v[56:59], v[172:175], v[198:201], v[56:59]
	v_mfma_f32_16x16x32_bf16 v[44:47], v[164:167], v[208:211], v[44:47]
	v_mfma_f32_16x16x32_bf16 v[40:43], v[172:175], v[208:211], v[40:43]
	v_mfma_f32_16x16x32_bf16 v[28:31], v[164:167], v[216:219], v[28:31]
	v_mfma_f32_16x16x32_bf16 v[24:27], v[172:175], v[216:219], v[24:27]
	v_mfma_f32_16x16x32_bf16 v[12:15], v[164:167], v[224:227], v[12:15]
	v_mfma_f32_16x16x32_bf16 v[8:11], v[172:175], v[224:227], v[8:11]
	s_setprio 0
	s_setprio 1
	v_mfma_f32_16x16x32_bf16 v[52:55], v[176:179], v[194:197], v[52:55]
	v_mfma_f32_16x16x32_bf16 v[48:51], v[184:187], v[194:197], v[48:51]
	v_mfma_f32_16x16x32_bf16 v[36:39], v[176:179], v[202:205], v[36:39]
	v_mfma_f32_16x16x32_bf16 v[32:35], v[184:187], v[202:205], v[32:35]
	v_mfma_f32_16x16x32_bf16 v[20:23], v[176:179], v[212:215], v[20:23]
	v_mfma_f32_16x16x32_bf16 v[16:19], v[184:187], v[212:215], v[16:19]
	v_mfma_f32_16x16x32_bf16 v[4:7], v[176:179], v[220:223], v[4:7]
	v_mfma_f32_16x16x32_bf16 v[0:3], v[184:187], v[220:223], v[0:3]
	v_mfma_f32_16x16x32_bf16 v[52:55], v[180:183], v[198:201], v[52:55]
	v_mfma_f32_16x16x32_bf16 v[48:51], v[190:193], v[198:201], v[48:51]
	v_mfma_f32_16x16x32_bf16 v[36:39], v[180:183], v[208:211], v[36:39]
	v_mfma_f32_16x16x32_bf16 v[32:35], v[190:193], v[208:211], v[32:35]
	v_mfma_f32_16x16x32_bf16 v[20:23], v[180:183], v[216:219], v[20:23]
	v_mfma_f32_16x16x32_bf16 v[16:19], v[190:193], v[216:219], v[16:19]
	v_mfma_f32_16x16x32_bf16 v[4:7], v[180:183], v[224:227], v[4:7]
	v_mfma_f32_16x16x32_bf16 v[0:3], v[190:193], v[224:227], v[0:3]
	s_setprio 0
	s_barrier
	s_add_i32 s86, 0, 0x18000
	s_add_i32 s87, 0, 0x1c000
	v_add_u32_e32 v172, s86, v159
	v_add_u32_e32 v190, s87, v159
	ds_read_b128 v[144:147], v172
	ds_read_b128 v[164:167], v172 offset:1024
	ds_read_b128 v[168:171], v172 offset:2048
	ds_read_b128 v[172:175], v172 offset:3072
	ds_read_b128 v[176:179], v190
	ds_read_b128 v[180:183], v190 offset:1024
	ds_read_b128 v[184:187], v190 offset:2048
	ds_read_b128 v[190:193], v190 offset:3072
	s_add_u32 s74, s74, 0x80000
	s_addc_u32 s75, s75, 0
	s_mov_b32 m0, s63
	v_lshl_add_u64 v[234:235], s[74:75], 0, v[128:129]
	ds_read_b128 v[194:197], v163 offset:32768
	ds_read_b128 v[198:201], v163 offset:33792
	ds_read_b128 v[202:205], v163 offset:34816
	ds_read_b128 v[208:211], v163 offset:35840
	ds_read_b128 v[212:215], v163 offset:36864
	ds_read_b128 v[216:219], v163 offset:37888
	ds_read_b128 v[220:223], v163 offset:38912
	ds_read_b128 v[224:227], v163 offset:39936
	global_load_lds_dwordx4 v[234:235], off
	v_lshl_add_u64 v[234:235], s[74:75], 0, v[132:133]
	s_mov_b32 m0, s64
	s_nop 0
	global_load_lds_dwordx4 v[234:235], off
	s_waitcnt vmcnt(8)
	s_waitcnt lgkmcnt(0)
	s_barrier
	s_setprio 1
	s_waitcnt lgkmcnt(0)
	v_mfma_f32_16x16x32_bf16 v[124:127], v[144:147], v[194:197], v[124:127]
	v_mfma_f32_16x16x32_bf16 v[120:123], v[168:171], v[194:197], v[120:123]
	v_mfma_f32_16x16x32_bf16 v[108:111], v[144:147], v[202:205], v[108:111]
	v_mfma_f32_16x16x32_bf16 v[104:107], v[168:171], v[202:205], v[104:107]
	v_mfma_f32_16x16x32_bf16 v[92:95], v[144:147], v[212:215], v[92:95]
	v_mfma_f32_16x16x32_bf16 v[88:91], v[168:171], v[212:215], v[88:91]
	v_mfma_f32_16x16x32_bf16 v[76:79], v[144:147], v[220:223], v[76:79]
	v_mfma_f32_16x16x32_bf16 v[72:75], v[168:171], v[220:223], v[72:75]
	v_mfma_f32_16x16x32_bf16 v[124:127], v[164:167], v[198:201], v[124:127]
	v_mfma_f32_16x16x32_bf16 v[120:123], v[172:175], v[198:201], v[120:123]
	v_mfma_f32_16x16x32_bf16 v[108:111], v[164:167], v[208:211], v[108:111]
	v_mfma_f32_16x16x32_bf16 v[104:107], v[172:175], v[208:211], v[104:107]
	v_mfma_f32_16x16x32_bf16 v[92:95], v[164:167], v[216:219], v[92:95]
	v_mfma_f32_16x16x32_bf16 v[88:91], v[172:175], v[216:219], v[88:91]
	v_mfma_f32_16x16x32_bf16 v[76:79], v[164:167], v[224:227], v[76:79]
	v_mfma_f32_16x16x32_bf16 v[72:75], v[172:175], v[224:227], v[72:75]
	s_setprio 0
	s_setprio 1
	v_mfma_f32_16x16x32_bf16 v[116:119], v[176:179], v[194:197], v[116:119]
	v_mfma_f32_16x16x32_bf16 v[112:115], v[184:187], v[194:197], v[112:115]
	v_mfma_f32_16x16x32_bf16 v[100:103], v[176:179], v[202:205], v[100:103]
	v_mfma_f32_16x16x32_bf16 v[96:99], v[184:187], v[202:205], v[96:99]
	v_mfma_f32_16x16x32_bf16 v[84:87], v[176:179], v[212:215], v[84:87]
	v_mfma_f32_16x16x32_bf16 v[80:83], v[184:187], v[212:215], v[80:83]
	v_mfma_f32_16x16x32_bf16 v[68:71], v[176:179], v[220:223], v[68:71]
	v_mfma_f32_16x16x32_bf16 v[64:67], v[184:187], v[220:223], v[64:67]
	v_mfma_f32_16x16x32_bf16 v[116:119], v[180:183], v[198:201], v[116:119]
	v_mfma_f32_16x16x32_bf16 v[112:115], v[190:193], v[198:201], v[112:115]
	v_mfma_f32_16x16x32_bf16 v[100:103], v[180:183], v[208:211], v[100:103]
	v_mfma_f32_16x16x32_bf16 v[96:99], v[190:193], v[208:211], v[96:99]
	v_mfma_f32_16x16x32_bf16 v[84:87], v[180:183], v[216:219], v[84:87]
	v_mfma_f32_16x16x32_bf16 v[80:83], v[190:193], v[216:219], v[80:83]
	v_mfma_f32_16x16x32_bf16 v[68:71], v[180:183], v[224:227], v[68:71]
	v_mfma_f32_16x16x32_bf16 v[64:67], v[190:193], v[224:227], v[64:67]
	s_setprio 0
	s_barrier
; #define PG8_STAGE(bufoff, gbase, voff) do { _Pragma("unroll") for (int _i = 0; _i < 2; ++_i) \
;         __builtin_amdgcn_global_load_lds((const unsigned*)((const char*)(gbase) + (voff)[_i]), (PG8_LAS unsigned*)(lds + (bufoff) + ldsw + _i * 8192), 16, 0, 0); } while (0)
; #define PG8_LDA(dst, b, h) do { _Pragma("unroll") for (int m = 0; m < 4; ++m) _Pragma("unroll") for (int k = 0; k < 2; ++k) dst[m][k] = *(const PG8_LAS bf16x8*)(lds + PG8_SA(b, h) + aoff + m * 2048 + k * 1024); } while (0)
; #define PG8_MMA(ai, bj, At, Bt) do { __builtin_amdgcn_s_setprio(1); _Pragma("unroll") for (int m = 0; m < 4; ++m) _Pragma("unroll") for (int n = 0; n < 2; ++n) _Pragma("unroll") for (int k = 0; k < 2; ++k) \
;         acc[ai][bj][m][n] = __builtin_amdgcn_mfma_f32_16x16x32_bf16(Bt[n][k], At[m][k], acc[ai][bj][m][n], 0, 0, 0); __builtin_amdgcn_s_setprio(0); } while (0)
; #define PG8_WAIT_V(n) asm volatile("s_waitcnt vmcnt(" #n ")" ::: "memory")
; #define PG8_WAIT_L(n) asm volatile("s_waitcnt lgkmcnt(" #n ")" ::: "memory")
; #define PG8_BAR __builtin_amdgcn_s_barrier()
; #define PG8_SCHED __builtin_amdgcn_sched_barrier(0)
; template <class Epi, bool BLKDIAG = false>
; __device__ __forceinline__ void gemm_phase(PG8_LAS unsigned char* lds, const Gemm g, const StaticOrder& S, const Epi& E) {
;     ...
;             PG8_LDA(At, 1, 1); PG8_STAGE(PG8_SB(1, 0), b3, voffB); PG8_STAGE(PG8_SB(1, 1), b3 + hstepB, voffB); PG8_STAGE(PG8_SA(1, 0), a3, voffA);
;             PG8_WAIT_V(8); PG8_WAIT_L(0); PG8_BAR; if (lo_) PG8_MMA(1, 0, At, B0); if (hi_) PG8_MMA(1, 1, At, B1); PG8_BAR; PG8_SCHED;
;         }
;         if (wr == 0) PG8_BAR;
	s_add_i32 s74, s86, s33
	v_lshl_add_u64 v[148:149], v[148:149], 0, s[12:13]
	s_mov_b32 m0, s74
	ds_read_b128 v[194:197], v163 offset:49152
	ds_read_b128 v[198:201], v163 offset:50176
	ds_read_b128 v[202:205], v163 offset:51200
	ds_read_b128 v[208:211], v163 offset:52224
	ds_read_b128 v[212:215], v163 offset:53248
	ds_read_b128 v[216:219], v163 offset:54272
	ds_read_b128 v[220:223], v163 offset:55296
	ds_read_b128 v[224:227], v163 offset:56320
	global_load_lds_dwordx4 v[148:149], off
	s_add_i32 m0, s74, 0x2000
	s_add_u32 s72, s72, 0x80080
	v_lshl_add_u64 v[148:149], v[228:229], 0, s[12:13]
	s_addc_u32 s73, s73, 0
	s_add_i32 s74, s87, s33
	global_load_lds_dwordx4 v[148:149], off
	v_lshl_add_u64 v[148:149], s[72:73], 0, v[130:131]
	s_mov_b32 m0, s74
	s_nop 0
	global_load_lds_dwordx4 v[148:149], off
	v_lshl_add_u64 v[148:149], s[72:73], 0, v[134:135]
	s_add_i32 m0, s74, 0x2000
	s_nop 0
	global_load_lds_dwordx4 v[148:149], off
	v_lshl_add_u64 v[148:149], v[230:231], 0, s[12:13]
	s_mov_b32 m0, s69
	s_nop 0
	global_load_lds_dwordx4 v[148:149], off
	v_lshl_add_u64 v[148:149], v[232:233], 0, s[12:13]
	s_mov_b32 m0, s76
	s_nop 0
	global_load_lds_dwordx4 v[148:149], off
	s_waitcnt vmcnt(8)
	s_waitcnt lgkmcnt(0)
	s_barrier
	s_setprio 1
	s_waitcnt lgkmcnt(0)
	v_mfma_f32_16x16x32_bf16 v[60:63], v[144:147], v[194:197], v[60:63]
	v_mfma_f32_16x16x32_bf16 v[56:59], v[168:171], v[194:197], v[56:59]
	v_mfma_f32_16x16x32_bf16 v[44:47], v[144:147], v[202:205], v[44:47]
	v_mfma_f32_16x16x32_bf16 v[40:43], v[168:171], v[202:205], v[40:43]
	v_mfma_f32_16x16x32_bf16 v[28:31], v[144:147], v[212:215], v[28:31]
	v_mfma_f32_16x16x32_bf16 v[24:27], v[168:171], v[212:215], v[24:27]
	v_mfma_f32_16x16x32_bf16 v[12:15], v[144:147], v[220:223], v[12:15]
	v_mfma_f32_16x16x32_bf16 v[8:11], v[168:171], v[220:223], v[8:11]
	v_mfma_f32_16x16x32_bf16 v[60:63], v[164:167], v[198:201], v[60:63]
	v_mfma_f32_16x16x32_bf16 v[56:59], v[172:175], v[198:201], v[56:59]
	v_mfma_f32_16x16x32_bf16 v[44:47], v[164:167], v[208:211], v[44:47]
	v_mfma_f32_16x16x32_bf16 v[40:43], v[172:175], v[208:211], v[40:43]
	v_mfma_f32_16x16x32_bf16 v[28:31], v[164:167], v[216:219], v[28:31]
	v_mfma_f32_16x16x32_bf16 v[24:27], v[172:175], v[216:219], v[24:27]
	v_mfma_f32_16x16x32_bf16 v[12:15], v[164:167], v[224:227], v[12:15]
	v_mfma_f32_16x16x32_bf16 v[8:11], v[172:175], v[224:227], v[8:11]
	s_setprio 0
	s_setprio 1
	v_mfma_f32_16x16x32_bf16 v[52:55], v[176:179], v[194:197], v[52:55]
	v_mfma_f32_16x16x32_bf16 v[48:51], v[184:187], v[194:197], v[48:51]
	v_mfma_f32_16x16x32_bf16 v[36:39], v[176:179], v[202:205], v[36:39]
	v_mfma_f32_16x16x32_bf16 v[32:35], v[184:187], v[202:205], v[32:35]
	v_mfma_f32_16x16x32_bf16 v[20:23], v[176:179], v[212:215], v[20:23]
	v_mfma_f32_16x16x32_bf16 v[16:19], v[184:187], v[212:215], v[16:19]
	v_mfma_f32_16x16x32_bf16 v[4:7], v[176:179], v[220:223], v[4:7]
	v_mfma_f32_16x16x32_bf16 v[0:3], v[184:187], v[220:223], v[0:3]
	v_mfma_f32_16x16x32_bf16 v[52:55], v[180:183], v[198:201], v[52:55]
	v_mfma_f32_16x16x32_bf16 v[48:51], v[190:193], v[198:201], v[48:51]
	v_mfma_f32_16x16x32_bf16 v[36:39], v[180:183], v[208:211], v[36:39]
	v_mfma_f32_16x16x32_bf16 v[32:35], v[190:193], v[208:211], v[32:35]
	v_mfma_f32_16x16x32_bf16 v[20:23], v[180:183], v[216:219], v[20:23]
	v_mfma_f32_16x16x32_bf16 v[16:19], v[190:193], v[216:219], v[16:19]
	v_mfma_f32_16x16x32_bf16 v[4:7], v[180:183], v[224:227], v[4:7]
	v_mfma_f32_16x16x32_bf16 v[0:3], v[190:193], v[224:227], v[0:3]
	s_setprio 0
	s_add_i32 s85, s85, 2
	s_add_u32 s70, s70, 0x100
	s_addc_u32 s71, s71, 0
	s_add_u32 s83, s83, 0x100
	s_addc_u32 s84, s84, 0
	s_cmp_gt_u32 s85, 29
	s_barrier
	s_cbranch_scc0 .LBB0_1000
	s_and_b64 vcc, exec, s[14:15]
	s_cbranch_vccz .LBB0_1003
	s_barrier

; #define PG8_STAGE(bufoff, gbase, voff) do { _Pragma("unroll") for (int _i = 0; _i < 2; ++_i) \
;         __builtin_amdgcn_global_load_lds((const unsigned*)((const char*)(gbase) + (voff)[_i]), (PG8_LAS unsigned*)(lds + (bufoff) + ldsw + _i * 8192), 16, 0, 0); } while (0)
; #define PG8_LDA(dst, b, h) do { _Pragma("unroll") for (int m = 0; m < 4; ++m) _Pragma("unroll") for (int k = 0; k < 2; ++k) dst[m][k] = *(const PG8_LAS bf16x8*)(lds + PG8_SA(b, h) + aoff + m * 2048 + k * 1024); } while (0)
; #define PG8_LDB(dst, b, h) do { _Pragma("unroll") for (int n = 0; n < 2; ++n) _Pragma("unroll") for (int k = 0; k < 2; ++k) dst[n][k] = *(const PG8_LAS bf16x8*)(lds + PG8_SB(b, h) + boff + n * 2048 + k * 1024); } while (0)
; #define PG8_MMA(ai, bj, At, Bt) do { __builtin_amdgcn_s_setprio(1); _Pragma("unroll") for (int m = 0; m < 4; ++m) _Pragma("unroll") for (int n = 0; n < 2; ++n) _Pragma("unroll") for (int k = 0; k < 2; ++k) \
;         acc[ai][bj][m][n] = __builtin_amdgcn_mfma_f32_16x16x32_bf16(Bt[n][k], At[m][k], acc[ai][bj][m][n], 0, 0, 0); __builtin_amdgcn_s_setprio(0); } while (0)
; #define PG8_WAIT_V(n) asm volatile("s_waitcnt vmcnt(" #n ")" ::: "memory")
; #define PG8_WAIT_L(n) asm volatile("s_waitcnt lgkmcnt(" #n ")" ::: "memory")
; #define PG8_BAR __builtin_amdgcn_s_barrier()
; #define PG8_SCHED __builtin_amdgcn_sched_barrier(0)
; template <class Epi, bool BLKDIAG = false>
; __device__ __forceinline__ void gemm_phase(PG8_LAS unsigned char* lds, const Gemm g, const StaticOrder& S, const Epi& E) {
;     ...
;             const char* a1 = cA + (size_t)(t + 1) * kstep;
;             const char* a2 = last ? nA : cA + (size_t)(t + 2) * kstep; const char* b2 = last ? nB : cB + (size_t)(t + 2) * kstep;
;             const char* a3 = a2 + kstep; const char* b3 = b2 + kstep;
;             PG8_LDB(B0, 0, 0); PG8_LDB(B1, 0, 1); PG8_SCHED; PG8_LDA(At, 0, 0); PG8_STAGE(PG8_SA(1, 1), a1 + hstepA, voffA);
;             PG8_WAIT_V(8); PG8_WAIT_L(0); PG8_BAR; if (lo_) PG8_MMA(0, 0, At, B0); if (hi_) PG8_MMA(0, 1, At, B1); PG8_BAR; PG8_SCHED;
;             PG8_LDA(At, 0, 1); PG8_STAGE(PG8_SB(0, 0), b2, voffB); PG8_STAGE(PG8_SB(0, 1), b2 + hstepB, voffB); PG8_STAGE(PG8_SA(0, 0), a2, voffA);
;             PG8_WAIT_V(8); PG8_WAIT_L(0); PG8_BAR; if (lo_) PG8_MMA(1, 0, At, B0); if (hi_) PG8_MMA(1, 1, At, B1); PG8_BAR; PG8_SCHED;
.LBB0_1024:
	ds_read_b128 v[144:147], v150
	ds_read_b128 v[158:161], v150 offset:1024
	ds_read_b128 v[162:165], v150 offset:2048
	ds_read_b128 v[166:169], v150 offset:3072
	ds_read_b128 v[170:173], v151
	ds_read_b128 v[174:177], v151 offset:1024
	ds_read_b128 v[178:181], v151 offset:2048
	ds_read_b128 v[182:185], v151 offset:3072
	s_add_u32 s60, s56, 0xfff80080
	s_addc_u32 s61, s57, -1
	s_cmp_eq_u32 s77, 28
	s_cselect_b32 s67, s45, s61
	s_cselect_b32 s66, s73, s60
	s_cselect_b32 s61, s43, s76
	s_cselect_b32 s60, s74, s75
	v_lshl_add_u64 v[148:149], s[56:57], 0, v[136:137]
	s_add_i32 m0, s35, 0xc000
	ds_read_b128 v[190:193], v152
	ds_read_b128 v[194:197], v152 offset:1024
	ds_read_b128 v[198:201], v152 offset:2048
	ds_read_b128 v[202:205], v152 offset:3072
	ds_read_b128 v[208:211], v152 offset:4096
	ds_read_b128 v[212:215], v152 offset:5120
	ds_read_b128 v[216:219], v152 offset:6144
	ds_read_b128 v[220:223], v152 offset:7168
	global_load_lds_dwordx4 v[148:149], off
	v_lshl_add_u64 v[148:149], s[56:57], 0, v[138:139]
	s_add_i32 m0, s35, 0xe000
	s_nop 0
	global_load_lds_dwordx4 v[148:149], off
	s_waitcnt vmcnt(8)
	s_waitcnt lgkmcnt(0)
	s_barrier
	s_setprio 1
	s_waitcnt lgkmcnt(0)
	v_mfma_f32_16x16x32_bf16 v[124:127], v[144:147], v[190:193], v[124:127]
	v_mfma_f32_16x16x32_bf16 v[120:123], v[162:165], v[190:193], v[120:123]
	v_mfma_f32_16x16x32_bf16 v[108:111], v[144:147], v[198:201], v[108:111]
	v_mfma_f32_16x16x32_bf16 v[104:107], v[162:165], v[198:201], v[104:107]
	v_mfma_f32_16x16x32_bf16 v[92:95], v[144:147], v[208:211], v[92:95]
	v_mfma_f32_16x16x32_bf16 v[88:91], v[162:165], v[208:211], v[88:91]
	v_mfma_f32_16x16x32_bf16 v[76:79], v[144:147], v[216:219], v[76:79]
	v_mfma_f32_16x16x32_bf16 v[72:75], v[162:165], v[216:219], v[72:75]
	v_mfma_f32_16x16x32_bf16 v[124:127], v[158:161], v[194:197], v[124:127]
	v_mfma_f32_16x16x32_bf16 v[120:123], v[166:169], v[194:197], v[120:123]
	v_mfma_f32_16x16x32_bf16 v[108:111], v[158:161], v[202:205], v[108:111]
	v_mfma_f32_16x16x32_bf16 v[104:107], v[166:169], v[202:205], v[104:107]
	v_mfma_f32_16x16x32_bf16 v[92:95], v[158:161], v[212:215], v[92:95]
	v_mfma_f32_16x16x32_bf16 v[88:91], v[166:169], v[212:215], v[88:91]
	v_mfma_f32_16x16x32_bf16 v[76:79], v[158:161], v[220:223], v[76:79]
	v_mfma_f32_16x16x32_bf16 v[72:75], v[166:169], v[220:223], v[72:75]
	s_setprio 0
	s_setprio 1
	v_mfma_f32_16x16x32_bf16 v[116:119], v[170:173], v[190:193], v[116:119]
	v_mfma_f32_16x16x32_bf16 v[112:115], v[178:181], v[190:193], v[112:115]
	v_mfma_f32_16x16x32_bf16 v[100:103], v[170:173], v[198:201], v[100:103]
	v_mfma_f32_16x16x32_bf16 v[96:99], v[178:181], v[198:201], v[96:99]
	v_mfma_f32_16x16x32_bf16 v[84:87], v[170:173], v[208:211], v[84:87]
	v_mfma_f32_16x16x32_bf16 v[80:83], v[178:181], v[208:211], v[80:83]
	v_mfma_f32_16x16x32_bf16 v[68:71], v[170:173], v[216:219], v[68:71]
	v_mfma_f32_16x16x32_bf16 v[64:67], v[178:181], v[216:219], v[64:67]
	v_mfma_f32_16x16x32_bf16 v[116:119], v[174:177], v[194:197], v[116:119]
	v_mfma_f32_16x16x32_bf16 v[112:115], v[182:185], v[194:197], v[112:115]
	v_mfma_f32_16x16x32_bf16 v[100:103], v[174:177], v[202:205], v[100:103]
	v_mfma_f32_16x16x32_bf16 v[96:99], v[182:185], v[202:205], v[96:99]
	v_mfma_f32_16x16x32_bf16 v[84:87], v[174:177], v[212:215], v[84:87]
	v_mfma_f32_16x16x32_bf16 v[80:83], v[182:185], v[212:215], v[80:83]
	v_mfma_f32_16x16x32_bf16 v[68:71], v[174:177], v[220:223], v[68:71]
	v_mfma_f32_16x16x32_bf16 v[64:67], v[182:185], v[220:223], v[64:67]
	s_setprio 0
	s_barrier
	s_add_i32 s78, s70, s33
	v_lshl_add_u64 v[148:149], s[60:61], 0, v[130:131]
	s_mov_b32 m0, s78
	ds_read_b128 v[190:193], v152 offset:16384
	ds_read_b128 v[194:197], v152 offset:17408
	ds_read_b128 v[198:201], v152 offset:18432
	ds_read_b128 v[202:205], v152 offset:19456
	ds_read_b128 v[208:211], v152 offset:20480
	ds_read_b128 v[212:215], v152 offset:21504
	ds_read_b128 v[216:219], v152 offset:22528
	ds_read_b128 v[220:223], v152 offset:23552
	global_load_lds_dwordx4 v[148:149], off
	s_add_i32 m0, s78, 0x2000
	s_add_u32 s78, s60, 0x80000
	v_lshl_add_u64 v[186:187], s[60:61], 0, v[134:135]
	s_addc_u32 s79, s61, 0
	s_add_i32 s80, s71, s33
	global_load_lds_dwordx4 v[186:187], off
	v_lshl_add_u64 v[224:225], s[78:79], 0, v[130:131]
	s_mov_b32 m0, s80
	v_lshl_add_u64 v[226:227], s[66:67], 0, v[132:133]
	global_load_lds_dwordx4 v[224:225], off
	v_lshl_add_u64 v[224:225], s[78:79], 0, v[134:135]
	s_add_i32 m0, s80, 0x2000
	s_nop 0
	global_load_lds_dwordx4 v[224:225], off
	v_lshl_add_u64 v[224:225], s[66:67], 0, v[128:129]
	s_mov_b32 m0, s35
	s_nop 0
	global_load_lds_dwordx4 v[224:225], off
	s_mov_b32 m0, s51
	s_nop 0
	global_load_lds_dwordx4 v[226:227], off
	s_waitcnt vmcnt(8)
	s_waitcnt lgkmcnt(0)
	s_barrier
; #define PG8_STAGE(bufoff, gbase, voff) do { _Pragma("unroll") for (int _i = 0; _i < 2; ++_i) \
;         __builtin_amdgcn_global_load_lds((const unsigned*)((const char*)(gbase) + (voff)[_i]), (PG8_LAS unsigned*)(lds + (bufoff) + ldsw + _i * 8192), 16, 0, 0); } while (0)
; #define PG8_LDA(dst, b, h) do { _Pragma("unroll") for (int m = 0; m < 4; ++m) _Pragma("unroll") for (int k = 0; k < 2; ++k) dst[m][k] = *(const PG8_LAS bf16x8*)(lds + PG8_SA(b, h) + aoff + m * 2048 + k * 1024); } while (0)
; #define PG8_LDB(dst, b, h) do { _Pragma("unroll") for (int n = 0; n < 2; ++n) _Pragma("unroll") for (int k = 0; k < 2; ++k) dst[n][k] = *(const PG8_LAS bf16x8*)(lds + PG8_SB(b, h) + boff + n * 2048 + k * 1024); } while (0)
; #define PG8_MMA(ai, bj, At, Bt) do { __builtin_amdgcn_s_setprio(1); _Pragma("unroll") for (int m = 0; m < 4; ++m) _Pragma("unroll") for (int n = 0; n < 2; ++n) _Pragma("unroll") for (int k = 0; k < 2; ++k) \
;         acc[ai][bj][m][n] = __builtin_amdgcn_mfma_f32_16x16x32_bf16(Bt[n][k], At[m][k], acc[ai][bj][m][n], 0, 0, 0); __builtin_amdgcn_s_setprio(0); } while (0)
; #define PG8_WAIT_V(n) asm volatile("s_waitcnt vmcnt(" #n ")" ::: "memory")
; #define PG8_WAIT_L(n) asm volatile("s_waitcnt lgkmcnt(" #n ")" ::: "memory")
; #define PG8_BAR __builtin_amdgcn_s_barrier()
; #define PG8_SCHED __builtin_amdgcn_sched_barrier(0)
; template <class Epi, bool BLKDIAG = false>
; __device__ __forceinline__ void gemm_phase(PG8_LAS unsigned char* lds, const Gemm g, const StaticOrder& S, const Epi& E) {
;     ...
;             PG8_WAIT_V(8); PG8_WAIT_L(0); PG8_BAR; if (lo_) PG8_MMA(1, 0, At, B0); if (hi_) PG8_MMA(1, 1, At, B1); PG8_BAR; PG8_SCHED;
;             PG8_LDB(B0, 1, 0); PG8_LDB(B1, 1, 1); PG8_SCHED; PG8_LDA(At, 1, 0); PG8_STAGE(PG8_SA(0, 1), a2 + hstepA, voffA);
;             PG8_WAIT_V(8); PG8_WAIT_L(0); PG8_BAR; if (lo_) PG8_MMA(0, 0, At, B0); if (hi_) PG8_MMA(0, 1, At, B1); PG8_BAR; PG8_SCHED;
	s_setprio 1
	s_waitcnt lgkmcnt(0)
	v_mfma_f32_16x16x32_bf16 v[60:63], v[144:147], v[190:193], v[60:63]
	v_mfma_f32_16x16x32_bf16 v[56:59], v[162:165], v[190:193], v[56:59]
	v_mfma_f32_16x16x32_bf16 v[44:47], v[144:147], v[198:201], v[44:47]
	v_mfma_f32_16x16x32_bf16 v[40:43], v[162:165], v[198:201], v[40:43]
	v_mfma_f32_16x16x32_bf16 v[28:31], v[144:147], v[208:211], v[28:31]
	v_mfma_f32_16x16x32_bf16 v[24:27], v[162:165], v[208:211], v[24:27]
	v_mfma_f32_16x16x32_bf16 v[12:15], v[144:147], v[216:219], v[12:15]
	v_mfma_f32_16x16x32_bf16 v[8:11], v[162:165], v[216:219], v[8:11]
	v_mfma_f32_16x16x32_bf16 v[60:63], v[158:161], v[194:197], v[60:63]
	v_mfma_f32_16x16x32_bf16 v[56:59], v[166:169], v[194:197], v[56:59]
	v_mfma_f32_16x16x32_bf16 v[44:47], v[158:161], v[202:205], v[44:47]
	v_mfma_f32_16x16x32_bf16 v[40:43], v[166:169], v[202:205], v[40:43]
	v_mfma_f32_16x16x32_bf16 v[28:31], v[158:161], v[212:215], v[28:31]
	v_mfma_f32_16x16x32_bf16 v[24:27], v[166:169], v[212:215], v[24:27]
	v_mfma_f32_16x16x32_bf16 v[12:15], v[158:161], v[220:223], v[12:15]
	v_mfma_f32_16x16x32_bf16 v[8:11], v[166:169], v[220:223], v[8:11]
	s_setprio 0
	s_setprio 1
	v_mfma_f32_16x16x32_bf16 v[52:55], v[170:173], v[190:193], v[52:55]
	v_mfma_f32_16x16x32_bf16 v[48:51], v[178:181], v[190:193], v[48:51]
	v_mfma_f32_16x16x32_bf16 v[36:39], v[170:173], v[198:201], v[36:39]
	v_mfma_f32_16x16x32_bf16 v[32:35], v[178:181], v[198:201], v[32:35]
	v_mfma_f32_16x16x32_bf16 v[20:23], v[170:173], v[208:211], v[20:23]
	v_mfma_f32_16x16x32_bf16 v[16:19], v[178:181], v[208:211], v[16:19]
	v_mfma_f32_16x16x32_bf16 v[4:7], v[170:173], v[216:219], v[4:7]
	v_mfma_f32_16x16x32_bf16 v[0:3], v[178:181], v[216:219], v[0:3]
	v_mfma_f32_16x16x32_bf16 v[52:55], v[174:177], v[194:197], v[52:55]
	v_mfma_f32_16x16x32_bf16 v[48:51], v[182:185], v[194:197], v[48:51]
	v_mfma_f32_16x16x32_bf16 v[36:39], v[174:177], v[202:205], v[36:39]
	v_mfma_f32_16x16x32_bf16 v[32:35], v[182:185], v[202:205], v[32:35]
	v_mfma_f32_16x16x32_bf16 v[20:23], v[174:177], v[212:215], v[20:23]
	v_mfma_f32_16x16x32_bf16 v[16:19], v[182:185], v[212:215], v[16:19]
	v_mfma_f32_16x16x32_bf16 v[4:7], v[174:177], v[220:223], v[4:7]
	v_mfma_f32_16x16x32_bf16 v[0:3], v[182:185], v[220:223], v[0:3]
	s_setprio 0
	s_barrier
	s_add_i32 s78, 0, 0x18000
	v_add_u32_e32 v154, s78, v156
	s_add_i32 s79, 0, 0x1c000
	ds_read_b128 v[144:147], v154
	ds_read_b128 v[158:161], v154 offset:1024
	ds_read_b128 v[162:165], v154 offset:2048
	ds_read_b128 v[166:169], v154 offset:3072
	v_add_u32_e32 v154, s79, v156
	ds_read_b128 v[170:173], v154
	ds_read_b128 v[174:177], v154 offset:1024
	ds_read_b128 v[178:181], v154 offset:2048
	ds_read_b128 v[182:185], v154 offset:3072
	s_add_u32 s66, s66, 0x80000
	s_addc_u32 s67, s67, 0
	s_mov_b32 m0, s62
	v_lshl_add_u64 v[228:229], s[66:67], 0, v[128:129]
	ds_read_b128 v[190:193], v152 offset:32768
	ds_read_b128 v[194:197], v152 offset:33792
	ds_read_b128 v[198:201], v152 offset:34816
	ds_read_b128 v[202:205], v152 offset:35840
	ds_read_b128 v[208:211], v152 offset:36864
	ds_read_b128 v[212:215], v152 offset:37888
	ds_read_b128 v[216:219], v152 offset:38912
	ds_read_b128 v[220:223], v152 offset:39936
	global_load_lds_dwordx4 v[228:229], off
	v_lshl_add_u64 v[228:229], s[66:67], 0, v[132:133]
	s_mov_b32 m0, s63
	s_nop 0
	global_load_lds_dwordx4 v[228:229], off
	s_waitcnt vmcnt(8)
	s_waitcnt lgkmcnt(0)
	s_barrier
	s_setprio 1
	s_waitcnt lgkmcnt(0)
	v_mfma_f32_16x16x32_bf16 v[124:127], v[144:147], v[190:193], v[124:127]
	v_mfma_f32_16x16x32_bf16 v[120:123], v[162:165], v[190:193], v[120:123]
	v_mfma_f32_16x16x32_bf16 v[108:111], v[144:147], v[198:201], v[108:111]
	v_mfma_f32_16x16x32_bf16 v[104:107], v[162:165], v[198:201], v[104:107]
	v_mfma_f32_16x16x32_bf16 v[92:95], v[144:147], v[208:211], v[92:95]
	v_mfma_f32_16x16x32_bf16 v[88:91], v[162:165], v[208:211], v[88:91]
	v_mfma_f32_16x16x32_bf16 v[76:79], v[144:147], v[216:219], v[76:79]
	v_mfma_f32_16x16x32_bf16 v[72:75], v[162:165], v[216:219], v[72:75]
	v_mfma_f32_16x16x32_bf16 v[124:127], v[158:161], v[194:197], v[124:127]
	v_mfma_f32_16x16x32_bf16 v[120:123], v[166:169], v[194:197], v[120:123]
	v_mfma_f32_16x16x32_bf16 v[108:111], v[158:161], v[202:205], v[108:111]
	v_mfma_f32_16x16x32_bf16 v[104:107], v[166:169], v[202:205], v[104:107]
	v_mfma_f32_16x16x32_bf16 v[92:95], v[158:161], v[212:215], v[92:95]
	v_mfma_f32_16x16x32_bf16 v[88:91], v[166:169], v[212:215], v[88:91]
	v_mfma_f32_16x16x32_bf16 v[76:79], v[158:161], v[220:223], v[76:79]
	v_mfma_f32_16x16x32_bf16 v[72:75], v[166:169], v[220:223], v[72:75]
	s_setprio 0
	s_setprio 1
	v_mfma_f32_16x16x32_bf16 v[116:119], v[170:173], v[190:193], v[116:119]
	v_mfma_f32_16x16x32_bf16 v[112:115], v[178:181], v[190:193], v[112:115]
	v_mfma_f32_16x16x32_bf16 v[100:103], v[170:173], v[198:201], v[100:103]
	v_mfma_f32_16x16x32_bf16 v[96:99], v[178:181], v[198:201], v[96:99]
	v_mfma_f32_16x16x32_bf16 v[84:87], v[170:173], v[208:211], v[84:87]
	v_mfma_f32_16x16x32_bf16 v[80:83], v[178:181], v[208:211], v[80:83]
	v_mfma_f32_16x16x32_bf16 v[68:71], v[170:173], v[216:219], v[68:71]
	v_mfma_f32_16x16x32_bf16 v[64:67], v[178:181], v[216:219], v[64:67]
	v_mfma_f32_16x16x32_bf16 v[116:119], v[174:177], v[194:197], v[116:119]
	v_mfma_f32_16x16x32_bf16 v[112:115], v[182:185], v[194:197], v[112:115]
	v_mfma_f32_16x16x32_bf16 v[100:103], v[174:177], v[202:205], v[100:103]
	v_mfma_f32_16x16x32_bf16 v[96:99], v[182:185], v[202:205], v[96:99]
	v_mfma_f32_16x16x32_bf16 v[84:87], v[174:177], v[212:215], v[84:87]
	v_mfma_f32_16x16x32_bf16 v[80:83], v[182:185], v[212:215], v[80:83]
	v_mfma_f32_16x16x32_bf16 v[68:71], v[174:177], v[220:223], v[68:71]
	v_mfma_f32_16x16x32_bf16 v[64:67], v[182:185], v[220:223], v[64:67]
	s_setprio 0
	s_barrier
; #define PG8_STAGE(bufoff, gbase, voff) do { _Pragma("unroll") for (int _i = 0; _i < 2; ++_i) \
;         __builtin_amdgcn_global_load_lds((const unsigned*)((const char*)(gbase) + (voff)[_i]), (PG8_LAS unsigned*)(lds + (bufoff) + ldsw + _i * 8192), 16, 0, 0); } while (0)
; #define PG8_LDA(dst, b, h) do { _Pragma("unroll") for (int m = 0; m < 4; ++m) _Pragma("unroll") for (int k = 0; k < 2; ++k) dst[m][k] = *(const PG8_LAS bf16x8*)(lds + PG8_SA(b, h) + aoff + m * 2048 + k * 1024); } while (0)
; #define PG8_MMA(ai, bj, At, Bt) do { __builtin_amdgcn_s_setprio(1); _Pragma("unroll") for (int m = 0; m < 4; ++m) _Pragma("unroll") for (int n = 0; n < 2; ++n) _Pragma("unroll") for (int k = 0; k < 2; ++k) \
;         acc[ai][bj][m][n] = __builtin_amdgcn_mfma_f32_16x16x32_bf16(Bt[n][k], At[m][k], acc[ai][bj][m][n], 0, 0, 0); __builtin_amdgcn_s_setprio(0); } while (0)
; #define PG8_WAIT_V(n) asm volatile("s_waitcnt vmcnt(" #n ")" ::: "memory")
; #define PG8_WAIT_L(n) asm volatile("s_waitcnt lgkmcnt(" #n ")" ::: "memory")
; #define PG8_BAR __builtin_amdgcn_s_barrier()
; #define PG8_SCHED __builtin_amdgcn_sched_barrier(0)
; template <class Epi, bool BLKDIAG = false>
; __device__ __forceinline__ void gemm_phase(PG8_LAS unsigned char* lds, const Gemm g, const StaticOrder& S, const Epi& E) {
;     ...
;             PG8_LDA(At, 1, 1); PG8_STAGE(PG8_SB(1, 0), b3, voffB); PG8_STAGE(PG8_SB(1, 1), b3 + hstepB, voffB); PG8_STAGE(PG8_SA(1, 0), a3, voffA);
;             PG8_WAIT_V(8); PG8_WAIT_L(0); PG8_BAR; if (lo_) PG8_MMA(1, 0, At, B0); if (hi_) PG8_MMA(1, 1, At, B1); PG8_BAR; PG8_SCHED;
;         }
;         if (wr == 0) PG8_BAR;
	s_add_i32 s66, s78, s33
	v_lshl_add_u64 v[148:149], v[148:149], 0, s[10:11]
	s_mov_b32 m0, s66
	ds_read_b128 v[190:193], v152 offset:49152
	ds_read_b128 v[194:197], v152 offset:50176
	ds_read_b128 v[198:201], v152 offset:51200
	ds_read_b128 v[202:205], v152 offset:52224
	ds_read_b128 v[208:211], v152 offset:53248
	ds_read_b128 v[212:215], v152 offset:54272
	ds_read_b128 v[216:219], v152 offset:55296
	ds_read_b128 v[220:223], v152 offset:56320
	global_load_lds_dwordx4 v[148:149], off
	s_add_i32 m0, s66, 0x2000
	s_add_u32 s60, s60, 0x80080
	v_lshl_add_u64 v[148:149], v[186:187], 0, s[10:11]
	s_addc_u32 s61, s61, 0
	s_add_i32 s66, s79, s33
	global_load_lds_dwordx4 v[148:149], off
	v_lshl_add_u64 v[148:149], s[60:61], 0, v[130:131]
	s_mov_b32 m0, s66
	s_nop 0
	global_load_lds_dwordx4 v[148:149], off
	v_lshl_add_u64 v[148:149], s[60:61], 0, v[134:135]
	s_add_i32 m0, s66, 0x2000
	s_nop 0
	global_load_lds_dwordx4 v[148:149], off
	v_lshl_add_u64 v[148:149], v[224:225], 0, s[10:11]
	s_mov_b32 m0, s65
	s_nop 0
	global_load_lds_dwordx4 v[148:149], off
	v_lshl_add_u64 v[148:149], v[226:227], 0, s[10:11]
	s_mov_b32 m0, s68
	s_nop 0
	global_load_lds_dwordx4 v[148:149], off
	s_waitcnt vmcnt(8)
	s_waitcnt lgkmcnt(0)
	s_barrier
	s_setprio 1
	s_waitcnt lgkmcnt(0)
	v_mfma_f32_16x16x32_bf16 v[60:63], v[144:147], v[190:193], v[60:63]
	v_mfma_f32_16x16x32_bf16 v[56:59], v[162:165], v[190:193], v[56:59]
	v_mfma_f32_16x16x32_bf16 v[44:47], v[144:147], v[198:201], v[44:47]
	v_mfma_f32_16x16x32_bf16 v[40:43], v[162:165], v[198:201], v[40:43]
	v_mfma_f32_16x16x32_bf16 v[28:31], v[144:147], v[208:211], v[28:31]
	v_mfma_f32_16x16x32_bf16 v[24:27], v[162:165], v[208:211], v[24:27]
	v_mfma_f32_16x16x32_bf16 v[12:15], v[144:147], v[216:219], v[12:15]
	v_mfma_f32_16x16x32_bf16 v[8:11], v[162:165], v[216:219], v[8:11]
	v_mfma_f32_16x16x32_bf16 v[60:63], v[158:161], v[194:197], v[60:63]
	v_mfma_f32_16x16x32_bf16 v[56:59], v[166:169], v[194:197], v[56:59]
	v_mfma_f32_16x16x32_bf16 v[44:47], v[158:161], v[202:205], v[44:47]
	v_mfma_f32_16x16x32_bf16 v[40:43], v[166:169], v[202:205], v[40:43]
	v_mfma_f32_16x16x32_bf16 v[28:31], v[158:161], v[212:215], v[28:31]
	v_mfma_f32_16x16x32_bf16 v[24:27], v[166:169], v[212:215], v[24:27]
	v_mfma_f32_16x16x32_bf16 v[12:15], v[158:161], v[220:223], v[12:15]
	v_mfma_f32_16x16x32_bf16 v[8:11], v[166:169], v[220:223], v[8:11]
	s_setprio 0
	s_setprio 1
	v_mfma_f32_16x16x32_bf16 v[52:55], v[170:173], v[190:193], v[52:55]
	v_mfma_f32_16x16x32_bf16 v[48:51], v[178:181], v[190:193], v[48:51]
	v_mfma_f32_16x16x32_bf16 v[36:39], v[170:173], v[198:201], v[36:39]
	v_mfma_f32_16x16x32_bf16 v[32:35], v[178:181], v[198:201], v[32:35]
	v_mfma_f32_16x16x32_bf16 v[20:23], v[170:173], v[208:211], v[20:23]
	v_mfma_f32_16x16x32_bf16 v[16:19], v[178:181], v[208:211], v[16:19]
	v_mfma_f32_16x16x32_bf16 v[4:7], v[170:173], v[216:219], v[4:7]
	v_mfma_f32_16x16x32_bf16 v[0:3], v[178:181], v[216:219], v[0:3]
	v_mfma_f32_16x16x32_bf16 v[52:55], v[174:177], v[194:197], v[52:55]
	v_mfma_f32_16x16x32_bf16 v[48:51], v[182:185], v[194:197], v[48:51]
	v_mfma_f32_16x16x32_bf16 v[36:39], v[174:177], v[202:205], v[36:39]
	v_mfma_f32_16x16x32_bf16 v[32:35], v[182:185], v[202:205], v[32:35]
	v_mfma_f32_16x16x32_bf16 v[20:23], v[174:177], v[212:215], v[20:23]
	v_mfma_f32_16x16x32_bf16 v[16:19], v[182:185], v[212:215], v[16:19]
	v_mfma_f32_16x16x32_bf16 v[4:7], v[174:177], v[220:223], v[4:7]
	v_mfma_f32_16x16x32_bf16 v[0:3], v[182:185], v[220:223], v[0:3]
	s_setprio 0
	s_add_i32 s77, s77, 2
	s_add_u32 s56, s56, 0x100
	s_addc_u32 s57, s57, 0
	s_add_u32 s75, s75, 0x100
	s_addc_u32 s76, s76, 0
	s_cmp_gt_u32 s77, 29
	s_barrier
	s_cbranch_scc0 .LBB0_1024
	s_and_b64 vcc, exec, s[12:13]
	s_cbranch_vccz .LBB0_1027
	s_barrier

; #define PG8_STAGE(bufoff, gbase, voff) do { _Pragma("unroll") for (int _i = 0; _i < 2; ++_i) \
;         __builtin_amdgcn_global_load_lds((const unsigned*)((const char*)(gbase) + (voff)[_i]), (PG8_LAS unsigned*)(lds + (bufoff) + ldsw + _i * 8192), 16, 0, 0); } while (0)
; #define PG8_LDA(dst, b, h) do { _Pragma("unroll") for (int m = 0; m < 4; ++m) _Pragma("unroll") for (int k = 0; k < 2; ++k) dst[m][k] = *(const PG8_LAS bf16x8*)(lds + PG8_SA(b, h) + aoff + m * 2048 + k * 1024); } while (0)
; #define PG8_LDB(dst, b, h) do { _Pragma("unroll") for (int n = 0; n < 2; ++n) _Pragma("unroll") for (int k = 0; k < 2; ++k) dst[n][k] = *(const PG8_LAS bf16x8*)(lds + PG8_SB(b, h) + boff + n * 2048 + k * 1024); } while (0)
; #define PG8_MMA(ai, bj, At, Bt) do { __builtin_amdgcn_s_setprio(1); _Pragma("unroll") for (int m = 0; m < 4; ++m) _Pragma("unroll") for (int n = 0; n < 2; ++n) _Pragma("unroll") for (int k = 0; k < 2; ++k) \
;         acc[ai][bj][m][n] = __builtin_amdgcn_mfma_f32_16x16x32_bf16(Bt[n][k], At[m][k], acc[ai][bj][m][n], 0, 0, 0); __builtin_amdgcn_s_setprio(0); } while (0)
; #define PG8_WAIT_V(n) asm volatile("s_waitcnt vmcnt(" #n ")" ::: "memory")
; #define PG8_WAIT_L(n) asm volatile("s_waitcnt lgkmcnt(" #n ")" ::: "memory")
; #define PG8_BAR __builtin_amdgcn_s_barrier()
; #define PG8_SCHED __builtin_amdgcn_sched_barrier(0)
; template <class Epi, bool BLKDIAG = false>
; __device__ __forceinline__ void gemm_phase(PG8_LAS unsigned char* lds, const Gemm g, const StaticOrder& S, const Epi& E) {
;     ...
;             const char* a1 = cA + (size_t)(t + 1) * kstep;
;             const char* a2 = last ? nA : cA + (size_t)(t + 2) * kstep; const char* b2 = last ? nB : cB + (size_t)(t + 2) * kstep;
;             const char* a3 = a2 + kstep; const char* b3 = b2 + kstep;
;             PG8_LDB(B0, 0, 0); PG8_LDB(B1, 0, 1); PG8_SCHED; PG8_LDA(At, 0, 0); PG8_STAGE(PG8_SA(1, 1), a1 + hstepA, voffA);
;             PG8_WAIT_V(8); PG8_WAIT_L(0); PG8_BAR; if (lo_) PG8_MMA(0, 0, At, B0); if (hi_) PG8_MMA(0, 1, At, B1); PG8_BAR; PG8_SCHED;
;             PG8_LDA(At, 0, 1); PG8_STAGE(PG8_SB(0, 0), b2, voffB); PG8_STAGE(PG8_SB(0, 1), b2 + hstepB, voffB); PG8_STAGE(PG8_SA(0, 0), a2, voffA);
;             PG8_WAIT_V(8); PG8_WAIT_L(0); PG8_BAR; if (lo_) PG8_MMA(1, 0, At, B0); if (hi_) PG8_MMA(1, 1, At, B1); PG8_BAR; PG8_SCHED;
.LBB0_1061:
	ds_read_b128 v[152:155], v149
	ds_read_b128 v[156:159], v149 offset:1024
	ds_read_b128 v[160:163], v149 offset:2048
	ds_read_b128 v[164:167], v149 offset:3072
	ds_read_b128 v[168:171], v150
	ds_read_b128 v[172:175], v150 offset:1024
	ds_read_b128 v[176:179], v150 offset:2048
	ds_read_b128 v[180:183], v150 offset:3072
	s_add_u32 s44, s42, 0xfff80080
	s_addc_u32 s45, s43, -1
	s_cmp_eq_u32 s66, 28
	s_cselect_b32 s47, s27, s45
	s_cselect_b32 s46, s62, s44
	s_cselect_b32 s45, s23, s65
	s_cselect_b32 s44, s63, s64
	v_lshl_add_u64 v[144:145], s[42:43], 0, v[136:137]
	s_add_i32 m0, s33, 0xc000
	ds_read_b128 v[184:187], v151
	ds_read_b128 v[190:193], v151 offset:1024
	ds_read_b128 v[194:197], v151 offset:2048
	ds_read_b128 v[198:201], v151 offset:3072
	ds_read_b128 v[202:205], v151 offset:4096
	ds_read_b128 v[208:211], v151 offset:5120
	ds_read_b128 v[212:215], v151 offset:6144
	ds_read_b128 v[216:219], v151 offset:7168
	global_load_lds_dwordx4 v[144:145], off
	v_lshl_add_u64 v[144:145], s[42:43], 0, v[138:139]
	s_add_i32 m0, s33, 0xe000
	s_nop 0
	global_load_lds_dwordx4 v[144:145], off
	s_waitcnt vmcnt(8)
	s_waitcnt lgkmcnt(0)
	s_barrier
	s_setprio 1
	s_waitcnt lgkmcnt(0)
	v_mfma_f32_16x16x32_bf16 v[124:127], v[152:155], v[184:187], v[124:127]
	v_mfma_f32_16x16x32_bf16 v[120:123], v[160:163], v[184:187], v[120:123]
	v_mfma_f32_16x16x32_bf16 v[116:119], v[152:155], v[194:197], v[116:119]
	v_mfma_f32_16x16x32_bf16 v[104:107], v[160:163], v[194:197], v[104:107]
	v_mfma_f32_16x16x32_bf16 v[100:103], v[152:155], v[202:205], v[100:103]
	v_mfma_f32_16x16x32_bf16 v[88:91], v[160:163], v[202:205], v[88:91]
	v_mfma_f32_16x16x32_bf16 v[84:87], v[152:155], v[212:215], v[84:87]
	v_mfma_f32_16x16x32_bf16 v[72:75], v[160:163], v[212:215], v[72:75]
	v_mfma_f32_16x16x32_bf16 v[124:127], v[156:159], v[190:193], v[124:127]
	v_mfma_f32_16x16x32_bf16 v[120:123], v[164:167], v[190:193], v[120:123]
	v_mfma_f32_16x16x32_bf16 v[116:119], v[156:159], v[198:201], v[116:119]
	v_mfma_f32_16x16x32_bf16 v[104:107], v[164:167], v[198:201], v[104:107]
	v_mfma_f32_16x16x32_bf16 v[100:103], v[156:159], v[208:211], v[100:103]
	v_mfma_f32_16x16x32_bf16 v[88:91], v[164:167], v[208:211], v[88:91]
	v_mfma_f32_16x16x32_bf16 v[84:87], v[156:159], v[216:219], v[84:87]
	v_mfma_f32_16x16x32_bf16 v[72:75], v[164:167], v[216:219], v[72:75]
	s_setprio 0
	s_setprio 1
	v_mfma_f32_16x16x32_bf16 v[112:115], v[168:171], v[184:187], v[112:115]
	v_mfma_f32_16x16x32_bf16 v[108:111], v[176:179], v[184:187], v[108:111]
	v_mfma_f32_16x16x32_bf16 v[96:99], v[168:171], v[194:197], v[96:99]
	v_mfma_f32_16x16x32_bf16 v[92:95], v[176:179], v[194:197], v[92:95]
	v_mfma_f32_16x16x32_bf16 v[80:83], v[168:171], v[202:205], v[80:83]
	v_mfma_f32_16x16x32_bf16 v[76:79], v[176:179], v[202:205], v[76:79]
	v_mfma_f32_16x16x32_bf16 v[68:71], v[168:171], v[212:215], v[68:71]
	v_mfma_f32_16x16x32_bf16 v[64:67], v[176:179], v[212:215], v[64:67]
	v_mfma_f32_16x16x32_bf16 v[112:115], v[172:175], v[190:193], v[112:115]
	v_mfma_f32_16x16x32_bf16 v[108:111], v[180:183], v[190:193], v[108:111]
	v_mfma_f32_16x16x32_bf16 v[96:99], v[172:175], v[198:201], v[96:99]
	v_mfma_f32_16x16x32_bf16 v[92:95], v[180:183], v[198:201], v[92:95]
	v_mfma_f32_16x16x32_bf16 v[80:83], v[172:175], v[208:211], v[80:83]
	v_mfma_f32_16x16x32_bf16 v[76:79], v[180:183], v[208:211], v[76:79]
	v_mfma_f32_16x16x32_bf16 v[68:71], v[172:175], v[216:219], v[68:71]
	v_mfma_f32_16x16x32_bf16 v[64:67], v[180:183], v[216:219], v[64:67]
	s_setprio 0
	s_barrier
	s_add_i32 s67, s57, s13
	v_lshl_add_u64 v[144:145], s[44:45], 0, v[130:131]
	s_mov_b32 m0, s67
	ds_read_b128 v[184:187], v151 offset:16384
	ds_read_b128 v[190:193], v151 offset:17408
	ds_read_b128 v[194:197], v151 offset:18432
	ds_read_b128 v[198:201], v151 offset:19456
	ds_read_b128 v[202:205], v151 offset:20480
	ds_read_b128 v[208:211], v151 offset:21504
	ds_read_b128 v[212:215], v151 offset:22528
	ds_read_b128 v[216:219], v151 offset:23552
	global_load_lds_dwordx4 v[144:145], off
	s_add_i32 m0, s67, 0x2000
	s_add_u32 s68, s44, 0x80000
	v_lshl_add_u64 v[220:221], s[44:45], 0, v[134:135]
	s_addc_u32 s69, s45, 0
	s_add_i32 s67, s60, s13
	global_load_lds_dwordx4 v[220:221], off
	v_lshl_add_u64 v[222:223], s[68:69], 0, v[130:131]
	s_mov_b32 m0, s67
	v_lshl_add_u64 v[224:225], s[46:47], 0, v[132:133]
	global_load_lds_dwordx4 v[222:223], off
	v_lshl_add_u64 v[222:223], s[68:69], 0, v[134:135]
	s_add_i32 m0, s67, 0x2000
	s_nop 0
	global_load_lds_dwordx4 v[222:223], off
	v_lshl_add_u64 v[222:223], s[46:47], 0, v[128:129]
	s_mov_b32 m0, s33
	s_nop 0
	global_load_lds_dwordx4 v[222:223], off
	s_mov_b32 m0, s35
	s_nop 0
	global_load_lds_dwordx4 v[224:225], off
	s_waitcnt vmcnt(8)
	s_waitcnt lgkmcnt(0)
	s_barrier
; #define PG8_STAGE(bufoff, gbase, voff) do { _Pragma("unroll") for (int _i = 0; _i < 2; ++_i) \
;         __builtin_amdgcn_global_load_lds((const unsigned*)((const char*)(gbase) + (voff)[_i]), (PG8_LAS unsigned*)(lds + (bufoff) + ldsw + _i * 8192), 16, 0, 0); } while (0)
; #define PG8_LDA(dst, b, h) do { _Pragma("unroll") for (int m = 0; m < 4; ++m) _Pragma("unroll") for (int k = 0; k < 2; ++k) dst[m][k] = *(const PG8_LAS bf16x8*)(lds + PG8_SA(b, h) + aoff + m * 2048 + k * 1024); } while (0)
; #define PG8_LDB(dst, b, h) do { _Pragma("unroll") for (int n = 0; n < 2; ++n) _Pragma("unroll") for (int k = 0; k < 2; ++k) dst[n][k] = *(const PG8_LAS bf16x8*)(lds + PG8_SB(b, h) + boff + n * 2048 + k * 1024); } while (0)
; #define PG8_MMA(ai, bj, At, Bt) do { __builtin_amdgcn_s_setprio(1); _Pragma("unroll") for (int m = 0; m < 4; ++m) _Pragma("unroll") for (int n = 0; n < 2; ++n) _Pragma("unroll") for (int k = 0; k < 2; ++k) \
;         acc[ai][bj][m][n] = __builtin_amdgcn_mfma_f32_16x16x32_bf16(Bt[n][k], At[m][k], acc[ai][bj][m][n], 0, 0, 0); __builtin_amdgcn_s_setprio(0); } while (0)
; #define PG8_WAIT_V(n) asm volatile("s_waitcnt vmcnt(" #n ")" ::: "memory")
; #define PG8_WAIT_L(n) asm volatile("s_waitcnt lgkmcnt(" #n ")" ::: "memory")
; #define PG8_BAR __builtin_amdgcn_s_barrier()
; #define PG8_SCHED __builtin_amdgcn_sched_barrier(0)
; template <class Epi, bool BLKDIAG = false>
; __device__ __forceinline__ void gemm_phase(PG8_LAS unsigned char* lds, const Gemm g, const StaticOrder& S, const Epi& E) {
;     ...
;             PG8_WAIT_V(8); PG8_WAIT_L(0); PG8_BAR; if (lo_) PG8_MMA(1, 0, At, B0); if (hi_) PG8_MMA(1, 1, At, B1); PG8_BAR; PG8_SCHED;
;             PG8_LDB(B0, 1, 0); PG8_LDB(B1, 1, 1); PG8_SCHED; PG8_LDA(At, 1, 0); PG8_STAGE(PG8_SA(0, 1), a2 + hstepA, voffA);
;             PG8_WAIT_V(8); PG8_WAIT_L(0); PG8_BAR; if (lo_) PG8_MMA(0, 0, At, B0); if (hi_) PG8_MMA(0, 1, At, B1); PG8_BAR; PG8_SCHED;
	s_setprio 1
	s_waitcnt lgkmcnt(0)
	v_mfma_f32_16x16x32_bf16 v[60:63], v[152:155], v[184:187], v[60:63]
	v_mfma_f32_16x16x32_bf16 v[56:59], v[160:163], v[184:187], v[56:59]
	v_mfma_f32_16x16x32_bf16 v[52:55], v[152:155], v[194:197], v[52:55]
	v_mfma_f32_16x16x32_bf16 v[40:43], v[160:163], v[194:197], v[40:43]
	v_mfma_f32_16x16x32_bf16 v[36:39], v[152:155], v[202:205], v[36:39]
	v_mfma_f32_16x16x32_bf16 v[24:27], v[160:163], v[202:205], v[24:27]
	v_mfma_f32_16x16x32_bf16 v[20:23], v[152:155], v[212:215], v[20:23]
	v_mfma_f32_16x16x32_bf16 v[8:11], v[160:163], v[212:215], v[8:11]
	v_mfma_f32_16x16x32_bf16 v[60:63], v[156:159], v[190:193], v[60:63]
	v_mfma_f32_16x16x32_bf16 v[56:59], v[164:167], v[190:193], v[56:59]
	v_mfma_f32_16x16x32_bf16 v[52:55], v[156:159], v[198:201], v[52:55]
	v_mfma_f32_16x16x32_bf16 v[40:43], v[164:167], v[198:201], v[40:43]
	v_mfma_f32_16x16x32_bf16 v[36:39], v[156:159], v[208:211], v[36:39]
	v_mfma_f32_16x16x32_bf16 v[24:27], v[164:167], v[208:211], v[24:27]
	v_mfma_f32_16x16x32_bf16 v[20:23], v[156:159], v[216:219], v[20:23]
	v_mfma_f32_16x16x32_bf16 v[8:11], v[164:167], v[216:219], v[8:11]
	s_setprio 0
	s_setprio 1
	v_mfma_f32_16x16x32_bf16 v[48:51], v[168:171], v[184:187], v[48:51]
	v_mfma_f32_16x16x32_bf16 v[44:47], v[176:179], v[184:187], v[44:47]
	v_mfma_f32_16x16x32_bf16 v[32:35], v[168:171], v[194:197], v[32:35]
	v_mfma_f32_16x16x32_bf16 v[28:31], v[176:179], v[194:197], v[28:31]
	v_mfma_f32_16x16x32_bf16 v[16:19], v[168:171], v[202:205], v[16:19]
	v_mfma_f32_16x16x32_bf16 v[12:15], v[176:179], v[202:205], v[12:15]
	v_mfma_f32_16x16x32_bf16 v[4:7], v[168:171], v[212:215], v[4:7]
	v_mfma_f32_16x16x32_bf16 v[0:3], v[176:179], v[212:215], v[0:3]
	v_mfma_f32_16x16x32_bf16 v[48:51], v[172:175], v[190:193], v[48:51]
	v_mfma_f32_16x16x32_bf16 v[44:47], v[180:183], v[190:193], v[44:47]
	v_mfma_f32_16x16x32_bf16 v[32:35], v[172:175], v[198:201], v[32:35]
	v_mfma_f32_16x16x32_bf16 v[28:31], v[180:183], v[198:201], v[28:31]
	v_mfma_f32_16x16x32_bf16 v[16:19], v[172:175], v[208:211], v[16:19]
	v_mfma_f32_16x16x32_bf16 v[12:15], v[180:183], v[208:211], v[12:15]
	v_mfma_f32_16x16x32_bf16 v[4:7], v[172:175], v[216:219], v[4:7]
	v_mfma_f32_16x16x32_bf16 v[0:3], v[180:183], v[216:219], v[0:3]
	s_setprio 0
	s_barrier
	s_add_i32 s67, 0, 0x18000
	s_add_i32 s68, 0, 0x1c000
	v_add_u32_e32 v164, s67, v147
	v_add_u32_e32 v180, s68, v147
	ds_read_b128 v[152:155], v164
	ds_read_b128 v[156:159], v164 offset:1024
	ds_read_b128 v[160:163], v164 offset:2048
	ds_read_b128 v[164:167], v164 offset:3072
	ds_read_b128 v[168:171], v180
	ds_read_b128 v[172:175], v180 offset:1024
	ds_read_b128 v[176:179], v180 offset:2048
	ds_read_b128 v[180:183], v180 offset:3072
	s_add_u32 s46, s46, 0x80000
	s_addc_u32 s47, s47, 0
	s_mov_b32 m0, s41
	v_lshl_add_u64 v[226:227], s[46:47], 0, v[128:129]
	ds_read_b128 v[184:187], v151 offset:32768
	ds_read_b128 v[190:193], v151 offset:33792
	ds_read_b128 v[194:197], v151 offset:34816
	ds_read_b128 v[198:201], v151 offset:35840
	ds_read_b128 v[202:205], v151 offset:36864
	ds_read_b128 v[208:211], v151 offset:37888
	ds_read_b128 v[212:215], v151 offset:38912
	ds_read_b128 v[216:219], v151 offset:39936
	global_load_lds_dwordx4 v[226:227], off
	v_lshl_add_u64 v[226:227], s[46:47], 0, v[132:133]
	s_mov_b32 m0, s48
	s_nop 0
	global_load_lds_dwordx4 v[226:227], off
	s_waitcnt vmcnt(8)
	s_waitcnt lgkmcnt(0)
	s_barrier
	s_setprio 1
	s_waitcnt lgkmcnt(0)
	v_mfma_f32_16x16x32_bf16 v[124:127], v[152:155], v[184:187], v[124:127]
	v_mfma_f32_16x16x32_bf16 v[120:123], v[160:163], v[184:187], v[120:123]
	v_mfma_f32_16x16x32_bf16 v[116:119], v[152:155], v[194:197], v[116:119]
	v_mfma_f32_16x16x32_bf16 v[104:107], v[160:163], v[194:197], v[104:107]
	v_mfma_f32_16x16x32_bf16 v[100:103], v[152:155], v[202:205], v[100:103]
	v_mfma_f32_16x16x32_bf16 v[88:91], v[160:163], v[202:205], v[88:91]
	v_mfma_f32_16x16x32_bf16 v[84:87], v[152:155], v[212:215], v[84:87]
	v_mfma_f32_16x16x32_bf16 v[72:75], v[160:163], v[212:215], v[72:75]
	v_mfma_f32_16x16x32_bf16 v[124:127], v[156:159], v[190:193], v[124:127]
	v_mfma_f32_16x16x32_bf16 v[120:123], v[164:167], v[190:193], v[120:123]
	v_mfma_f32_16x16x32_bf16 v[116:119], v[156:159], v[198:201], v[116:119]
	v_mfma_f32_16x16x32_bf16 v[104:107], v[164:167], v[198:201], v[104:107]
	v_mfma_f32_16x16x32_bf16 v[100:103], v[156:159], v[208:211], v[100:103]
	v_mfma_f32_16x16x32_bf16 v[88:91], v[164:167], v[208:211], v[88:91]
	v_mfma_f32_16x16x32_bf16 v[84:87], v[156:159], v[216:219], v[84:87]
	v_mfma_f32_16x16x32_bf16 v[72:75], v[164:167], v[216:219], v[72:75]
	s_setprio 0
	s_setprio 1
	v_mfma_f32_16x16x32_bf16 v[112:115], v[168:171], v[184:187], v[112:115]
	v_mfma_f32_16x16x32_bf16 v[108:111], v[176:179], v[184:187], v[108:111]
	v_mfma_f32_16x16x32_bf16 v[96:99], v[168:171], v[194:197], v[96:99]
	v_mfma_f32_16x16x32_bf16 v[92:95], v[176:179], v[194:197], v[92:95]
	v_mfma_f32_16x16x32_bf16 v[80:83], v[168:171], v[202:205], v[80:83]
	v_mfma_f32_16x16x32_bf16 v[76:79], v[176:179], v[202:205], v[76:79]
	v_mfma_f32_16x16x32_bf16 v[68:71], v[168:171], v[212:215], v[68:71]
	v_mfma_f32_16x16x32_bf16 v[64:67], v[176:179], v[212:215], v[64:67]
	v_mfma_f32_16x16x32_bf16 v[112:115], v[172:175], v[190:193], v[112:115]
	v_mfma_f32_16x16x32_bf16 v[108:111], v[180:183], v[190:193], v[108:111]
	v_mfma_f32_16x16x32_bf16 v[96:99], v[172:175], v[198:201], v[96:99]
	v_mfma_f32_16x16x32_bf16 v[92:95], v[180:183], v[198:201], v[92:95]
	v_mfma_f32_16x16x32_bf16 v[80:83], v[172:175], v[208:211], v[80:83]
	v_mfma_f32_16x16x32_bf16 v[76:79], v[180:183], v[208:211], v[76:79]
	v_mfma_f32_16x16x32_bf16 v[68:71], v[172:175], v[216:219], v[68:71]
	v_mfma_f32_16x16x32_bf16 v[64:67], v[180:183], v[216:219], v[64:67]
	s_setprio 0
	s_barrier
; #define PG8_STAGE(bufoff, gbase, voff) do { _Pragma("unroll") for (int _i = 0; _i < 2; ++_i) \
;         __builtin_amdgcn_global_load_lds((const unsigned*)((const char*)(gbase) + (voff)[_i]), (PG8_LAS unsigned*)(lds + (bufoff) + ldsw + _i * 8192), 16, 0, 0); } while (0)
; #define PG8_LDA(dst, b, h) do { _Pragma("unroll") for (int m = 0; m < 4; ++m) _Pragma("unroll") for (int k = 0; k < 2; ++k) dst[m][k] = *(const PG8_LAS bf16x8*)(lds + PG8_SA(b, h) + aoff + m * 2048 + k * 1024); } while (0)
; #define PG8_MMA(ai, bj, At, Bt) do { __builtin_amdgcn_s_setprio(1); _Pragma("unroll") for (int m = 0; m < 4; ++m) _Pragma("unroll") for (int n = 0; n < 2; ++n) _Pragma("unroll") for (int k = 0; k < 2; ++k) \
;         acc[ai][bj][m][n] = __builtin_amdgcn_mfma_f32_16x16x32_bf16(Bt[n][k], At[m][k], acc[ai][bj][m][n], 0, 0, 0); __builtin_amdgcn_s_setprio(0); } while (0)
; #define PG8_WAIT_V(n) asm volatile("s_waitcnt vmcnt(" #n ")" ::: "memory")
; #define PG8_WAIT_L(n) asm volatile("s_waitcnt lgkmcnt(" #n ")" ::: "memory")
; #define PG8_BAR __builtin_amdgcn_s_barrier()
; #define PG8_SCHED __builtin_amdgcn_sched_barrier(0)
; template <class Epi, bool BLKDIAG = false>
; __device__ __forceinline__ void gemm_phase(PG8_LAS unsigned char* lds, const Gemm g, const StaticOrder& S, const Epi& E) {
;     ...
;             PG8_LDA(At, 1, 1); PG8_STAGE(PG8_SB(1, 0), b3, voffB); PG8_STAGE(PG8_SB(1, 1), b3 + hstepB, voffB); PG8_STAGE(PG8_SA(1, 0), a3, voffA);
;             PG8_WAIT_V(8); PG8_WAIT_L(0); PG8_BAR; if (lo_) PG8_MMA(1, 0, At, B0); if (hi_) PG8_MMA(1, 1, At, B1); PG8_BAR; PG8_SCHED;
;         }
;         if (wr == 0) PG8_BAR;
	s_add_i32 s46, s67, s13
	v_lshl_add_u64 v[144:145], v[144:145], 0, s[8:9]
	s_mov_b32 m0, s46
	ds_read_b128 v[184:187], v151 offset:49152
	ds_read_b128 v[190:193], v151 offset:50176
	ds_read_b128 v[194:197], v151 offset:51200
	ds_read_b128 v[198:201], v151 offset:52224
	ds_read_b128 v[202:205], v151 offset:53248
	ds_read_b128 v[208:211], v151 offset:54272
	ds_read_b128 v[212:215], v151 offset:55296
	ds_read_b128 v[216:219], v151 offset:56320
	global_load_lds_dwordx4 v[144:145], off
	s_add_i32 m0, s46, 0x2000
	s_add_u32 s44, s44, 0x80080
	v_lshl_add_u64 v[144:145], v[220:221], 0, s[8:9]
	s_addc_u32 s45, s45, 0
	s_add_i32 s46, s68, s13
	global_load_lds_dwordx4 v[144:145], off
	v_lshl_add_u64 v[144:145], s[44:45], 0, v[130:131]
	s_mov_b32 m0, s46
	s_nop 0
	global_load_lds_dwordx4 v[144:145], off
	v_lshl_add_u64 v[144:145], s[44:45], 0, v[134:135]
	s_add_i32 m0, s46, 0x2000
	s_nop 0
	global_load_lds_dwordx4 v[144:145], off
	v_lshl_add_u64 v[144:145], v[222:223], 0, s[8:9]
	s_mov_b32 m0, s50
	s_nop 0
	global_load_lds_dwordx4 v[144:145], off
	v_lshl_add_u64 v[144:145], v[224:225], 0, s[8:9]
	s_mov_b32 m0, s51
	s_nop 0
	global_load_lds_dwordx4 v[144:145], off
	s_waitcnt vmcnt(8)
	s_waitcnt lgkmcnt(0)
	s_barrier
	s_setprio 1
	s_waitcnt lgkmcnt(0)
	v_mfma_f32_16x16x32_bf16 v[60:63], v[152:155], v[184:187], v[60:63]
	v_mfma_f32_16x16x32_bf16 v[56:59], v[160:163], v[184:187], v[56:59]
	v_mfma_f32_16x16x32_bf16 v[52:55], v[152:155], v[194:197], v[52:55]
	v_mfma_f32_16x16x32_bf16 v[40:43], v[160:163], v[194:197], v[40:43]
	v_mfma_f32_16x16x32_bf16 v[36:39], v[152:155], v[202:205], v[36:39]
	v_mfma_f32_16x16x32_bf16 v[24:27], v[160:163], v[202:205], v[24:27]
	v_mfma_f32_16x16x32_bf16 v[20:23], v[152:155], v[212:215], v[20:23]
	v_mfma_f32_16x16x32_bf16 v[8:11], v[160:163], v[212:215], v[8:11]
	v_mfma_f32_16x16x32_bf16 v[60:63], v[156:159], v[190:193], v[60:63]
	v_mfma_f32_16x16x32_bf16 v[56:59], v[164:167], v[190:193], v[56:59]
	v_mfma_f32_16x16x32_bf16 v[52:55], v[156:159], v[198:201], v[52:55]
	v_mfma_f32_16x16x32_bf16 v[40:43], v[164:167], v[198:201], v[40:43]
	v_mfma_f32_16x16x32_bf16 v[36:39], v[156:159], v[208:211], v[36:39]
	v_mfma_f32_16x16x32_bf16 v[24:27], v[164:167], v[208:211], v[24:27]
	v_mfma_f32_16x16x32_bf16 v[20:23], v[156:159], v[216:219], v[20:23]
	v_mfma_f32_16x16x32_bf16 v[8:11], v[164:167], v[216:219], v[8:11]
	s_setprio 0
	s_setprio 1
	v_mfma_f32_16x16x32_bf16 v[48:51], v[168:171], v[184:187], v[48:51]
	v_mfma_f32_16x16x32_bf16 v[44:47], v[176:179], v[184:187], v[44:47]
	v_mfma_f32_16x16x32_bf16 v[32:35], v[168:171], v[194:197], v[32:35]
	v_mfma_f32_16x16x32_bf16 v[28:31], v[176:179], v[194:197], v[28:31]
	v_mfma_f32_16x16x32_bf16 v[16:19], v[168:171], v[202:205], v[16:19]
	v_mfma_f32_16x16x32_bf16 v[12:15], v[176:179], v[202:205], v[12:15]
	v_mfma_f32_16x16x32_bf16 v[4:7], v[168:171], v[212:215], v[4:7]
	v_mfma_f32_16x16x32_bf16 v[0:3], v[176:179], v[212:215], v[0:3]
	v_mfma_f32_16x16x32_bf16 v[48:51], v[172:175], v[190:193], v[48:51]
	v_mfma_f32_16x16x32_bf16 v[44:47], v[180:183], v[190:193], v[44:47]
	v_mfma_f32_16x16x32_bf16 v[32:35], v[172:175], v[198:201], v[32:35]
	v_mfma_f32_16x16x32_bf16 v[28:31], v[180:183], v[198:201], v[28:31]
	v_mfma_f32_16x16x32_bf16 v[16:19], v[172:175], v[208:211], v[16:19]
	v_mfma_f32_16x16x32_bf16 v[12:15], v[180:183], v[208:211], v[12:15]
	v_mfma_f32_16x16x32_bf16 v[4:7], v[172:175], v[216:219], v[4:7]
	v_mfma_f32_16x16x32_bf16 v[0:3], v[180:183], v[216:219], v[0:3]
	s_setprio 0
	s_add_i32 s66, s66, 2
	s_add_u32 s42, s42, 0x100
	s_addc_u32 s43, s43, 0
	s_add_u32 s64, s64, 0x100
	s_addc_u32 s65, s65, 0
	s_cmp_gt_u32 s66, 29
	s_barrier
	s_cbranch_scc0 .LBB0_1061
	s_and_b64 vcc, exec, s[10:11]
	s_cbranch_vccz .LBB0_1064
	s_barrier
